# speedup vs baseline: 1.0043x; 1.0043x over previous
; #define LDK(DST, KQ) _Pragma("unroll") for (int kc = 0; kc < 4; ++kc) DST[kc] = *(const bf16x8*)(Ks + ((KQ) * 16 + fr) * 136 + kc * 32 + fq * 8)
; DEVINL void attn_item(const Params& p, int item, char* smem, int wv) {
;     ...
;   const size_t qtok = (size_t)b * SEQ + q0 + wid * 16 + fr;
;   bf16x8 qf[2][4];
; #pragma unroll
;   for (int hh = 0; hh < 2; ++hh)
; #pragma unroll
;     for (int kc = 0; kc < 4; ++kc)
;       qf[hh][kc] = *(const bf16x8*)(hb + qtok * HS + 2560 + (kvh * 2 + hh) * 128 + kc * 32 + fq * 8);
;   f32x4 o[2][8];
; #pragma unroll
;   for (int hh = 0; hh < 2; ++hh)
; #pragma unroll
;     for (int dt = 0; dt < 8; ++dt) o[hh][dt] = f32x4{0.f, 0.f, 0.f, 0.f};
;   float mrun[2] = {0.f, 0.f}, lsum[2] = {0.f, 0.f};
;   unsigned long long mw_next = bits[qtok * 64];
;   u32x4 rk[2], rv[2];
;   const u16* kg = hb + ((size_t)b * SEQ + (tid >> 4)) * HS + 3584 + kvh * 128 + (tid & 15) * 8;
;   const u16* vg = vT + ((size_t)(b * 4 + kvh) * 128 + (tid >> 3)) * SEQ + (tid & 7) * 8;
; #pragma unroll
;   for (int i = 0; i < 2; ++i) {
;     rk[i] = *(const u32x4*)(kg + (size_t)(32 * i) * HS);
;     rv[i] = *(const u32x4*)(vg + (size_t)(64 * i) * SEQ);
;   }
;   for (int kt = 0; kt < ntile; ++kt) {
; #pragma unroll
;     for (int i = 0; i < 2; ++i) {
;       *(u32x4*)(Ks + ((tid >> 4) + 32 * i) * 136 + (tid & 15) * 8) = rk[i];
;       *(u32x4*)(Vs + ((tid >> 3) + 64 * i) * 72 + (tid & 7) * 8) = rv[i];
;     }
;     __syncthreads();
;     if (kt + 1 < ntile) {
; #pragma unroll
;       for (int i = 0; i < 2; ++i) {
;         rk[i] = *(const u32x4*)(kg + (size_t)((kt + 1) * 64 + 32 * i) * HS);
;         rv[i] = *(const u32x4*)(vg + (size_t)(64 * i) * SEQ + (kt + 1) * 64);
;       }
;     }
;     const unsigned long long mw = mw_next;
;     if (kt + 1 < ntile) mw_next = bits[qtok * 64 + kt + 1];
;     if (kt * 64 <= qlast) {
;     f32x4 s[2][4];
;     bf16x8 kfa[4], kfb[4];
;     bf16x8 vfa[2], vfb[2];
;     ...
;     LDK(kfa, 0);
;     LDK(kfb, 1); MMS(kfa, 0);
;     LDK(kfa, 2); MMS(kfb, 1);
; DEVINL void phase_mix(const Params& p, int layer, char* smem, int wv, int rep) {
;     ...
;     for (;;) {
;       int it = next_item(ctr2, smem, wv);
;       if (it >= 512) break;
;       attn_item(p, it, smem, wv);
.LBB0_701:
	s_or_b64 exec, exec, s[0:1]
	s_waitcnt lgkmcnt(0)
	s_barrier
	ds_read_b32 v0, v170
	s_movk_i32 s0, 0x1ff
	s_waitcnt lgkmcnt(0)
	v_cmp_lt_i32_e32 vcc, s0, v0
	v_readfirstlane_b32 s5, v0
	s_mov_b64 s[0:1], -1
	s_cbranch_vccnz .LBB0_696
	v_mov_b32_e32 v120, v176
	s_ashr_i32 s29, s5, 4
	s_sub_i32 s30, 31, s29
	v_readfirstlane_b32 s0, v120
	s_lshl_b32 s1, s5, 10
	s_lshl_b32 s7, s30, 7
	s_ashr_i32 s31, s0, 2
	s_and_b32 s33, s1, 0x3000
	v_and_b32_e32 v60, 15, v120
	s_and_b32 s0, s31, -16
	s_add_i32 s8, s7, s33
	s_ashr_i32 s1, s0, 31
	v_or_b32_e32 v0, s8, v60
	s_waitcnt vmcnt(1)
	v_lshl_add_u64 v[156:157], v[0:1], 0, s[0:1]
	v_mov_b64_e32 v[2:3], s[62:63]
	v_mad_u64_u32 v[4:5], s[0:1], v156, s19, v[2:3]
	s_and_b32 s6, s5, 3
	v_mad_i32_i24 v5, v157, s19, v5
	v_and_b32_e32 v0, 48, v120
	v_lshl_add_u64 v[4:5], v[4:5], 0, v[0:1]
	s_lshl_b32 s8, s6, 9
	v_ashrrev_i32_e32 v14, 4, v120
	v_lshl_add_u64 v[8:9], v[4:5], 0, s[8:9]
	v_add_u32_e32 v4, s33, v14
	s_lshl_b32 s16, s6, 8
	s_mov_b32 s17, s9
	v_mad_i64_i32 v[2:3], s[0:1], v4, s19, v[2:3]
	v_lshlrev_b32_e32 v6, 4, v120
	v_lshl_add_u64 v[2:3], v[2:3], 0, s[16:17]
	v_and_b32_e32 v10, 0xf0, v6
	v_mov_b32_e32 v11, v1
	v_lshl_add_u64 v[116:117], v[2:3], 0, v[10:11]
	s_lshl_b32 s0, s5, 7
	v_ashrrev_i32_e32 v2, 3, v120
	s_and_b32 s8, s0, 0x780
	v_ashrrev_i32_e32 v3, 31, v2
	v_lshl_add_u64 v[4:5], v[2:3], 0, s[8:9]
	v_lshlrev_b64 v[4:5], 13, v[4:5]
	v_lshl_add_u64 v[4:5], s[82:83], 0, v[4:5]
	v_and_b32_e32 v12, 0x70, v6
	v_mov_b32_e32 v13, v1
	v_lshl_add_u64 v[158:159], v[4:5], 0, v[12:13]
	v_add_co_u32_e32 v4, vcc, s20, v116
	global_load_dwordx4 v[36:39], v[158:159], off
	s_nop 0
	v_addc_co_u32_e32 v5, vcc, 0, v117, vcc
	v_add_co_u32_e32 v6, vcc, s21, v116
	v_mul_lo_u32 v2, v2, s24
	s_nop 0
	v_addc_co_u32_e32 v7, vcc, 0, v117, vcc
	global_load_dwordx4 v[40:43], v[4:5], off offset:3072
	global_load_dwordx4 v[44:47], v[6:7], off offset:3072
	v_add_co_u32_e32 v52, vcc, s22, v158
	v_add_u32_e32 v11, 0, v12
	s_nop 0
	v_addc_co_u32_e32 v53, vcc, 0, v159, vcc
	global_load_dwordx4 v[48:51], v[52:53], off
	v_mul_lo_u32 v3, v14, s23
	v_add_u32_e32 v10, 0, v10
	v_and_b32_e32 v173, 64, v12
	v_bfe_u32 v11, v12, 4, 1
	v_lshl_or_b32 v173, v11, 5, v173
	v_bfe_u32 v11, v12, 5, 1
	v_lshl_or_b32 v173, v11, 3, v173
	v_add_u32_e32 v173, v173, v2
	v_add_co_u32_e64 v2, s[0:1], s20, v8
	v_lshl_add_u64 v[28:29], v[8:9], 0, s[10:11]
	v_add_u32_e32 v172, v10, v3
	v_lshlrev_b64 v[118:119], 9, v[156:157]
	v_add_co_u32_e32 v54, vcc, 0xa1000, v116
	v_addc_co_u32_e64 v3, s[0:1], 0, v9, s[0:1]
	global_load_dwordx4 v[4:7], v[28:29], off offset:64
	v_lshl_add_u64 v[56:57], s[80:81], 0, v[118:119]
	v_addc_co_u32_e32 v55, vcc, 0, v117, vcc
	global_load_dwordx4 v[8:11], v[28:29], off offset:128
	global_load_dwordx4 v[12:15], v[28:29], off offset:192
	global_load_dwordx4 v[16:19], v[28:29], off offset:256
	global_load_dwordx4 v[20:23], v[28:29], off offset:320
	global_load_dwordx4 v[24:27], v[28:29], off offset:384
	s_nop 0
	global_load_dwordx4 v[28:31], v[28:29], off offset:448
	s_nop 0
	global_load_dwordx4 v[32:35], v[2:3], off offset:1024
	s_nop 0
	global_load_dwordx2 v[2:3], v[56:57], off
	v_add_co_u32_e32 v58, vcc, 0xf1000, v116
	s_add_i32 s8, s31, s7
	s_nop 0
	v_addc_co_u32_e32 v59, vcc, 0, v117, vcc
	s_cmp_gt_i32 s8, -1
	s_mov_b64 s[0:1], -1
	s_waitcnt vmcnt(11)
	ds_write_b128 v172, v[40:43]
	ds_write_b64 v173, v[36:37] offset:17408
	ds_write_b64 v173, v[38:39] offset:17424
	s_waitcnt vmcnt(10)
	ds_write_b128 v172, v[44:47] offset:8704
	s_waitcnt vmcnt(9)
	ds_write_b64 v173, v[48:49] offset:26624
	ds_write_b64 v173, v[50:51] offset:26640
	s_waitcnt lgkmcnt(0)
	s_barrier
	global_load_dwordx4 v[44:47], v[58:59], off offset:3072
	global_load_dwordx4 v[36:39], v[54:55], off offset:3072
	global_load_dwordx4 v[48:51], v[52:53], off offset:128
	global_load_dwordx4 v[40:43], v[158:159], off offset:128
	global_load_dwordx2 v[162:163], v[56:57], off offset:8
	v_mad_u32_u24 v52, v60, s23, 0
	v_lshlrev_b32_e32 v53, 7, v60
	v_lshrrev_b32_e32 v54, 2, v120
	v_sub_u32_e32 v53, v52, v53
	v_and_b32_e32 v174, 12, v54
	v_add_u32_e32 v175, v52, v0
	v_lshl_add_u32 v177, v174, 2, v53
	s_cbranch_scc0 .LBB0_704
	ds_read_b128 v[52:55], v175
	ds_read_b128 v[56:59], v175 offset:64
	ds_read_b128 v[60:63], v175 offset:128
	ds_read_b128 v[64:67], v175 offset:192
	ds_read_b128 v[68:71], v175 offset:4352
	ds_read_b128 v[72:75], v175 offset:4416
	ds_read_b128 v[76:79], v175 offset:4480
	ds_read_b128 v[80:83], v175 offset:4544
	s_setprio 1
	s_mov_b32 s6, s4
	s_mov_b32 s7, s4
	s_mov_b32 s5, s4
	v_mov_b64_e32 v[86:87], s[6:7]
	v_mov_b64_e32 v[84:85], s[4:5]
	s_waitcnt vmcnt(6) lgkmcnt(7)
	s_nop 0
	v_mfma_f32_16x16x32_bf16 v[88:91], v[52:55], v[32:35], v[84:87]
	v_mfma_f32_16x16x32_bf16 v[52:55], v[52:55], v[16:19], v[84:87]
	s_waitcnt lgkmcnt(6)
	v_mfma_f32_16x16x32_bf16 v[88:91], v[56:59], v[4:7], v[88:91]
	v_mfma_f32_16x16x32_bf16 v[52:55], v[56:59], v[20:23], v[52:55]
	s_waitcnt lgkmcnt(5)
	v_mfma_f32_16x16x32_bf16 v[56:59], v[60:63], v[8:11], v[88:91]
	v_mfma_f32_16x16x32_bf16 v[52:55], v[60:63], v[24:27], v[52:55]
	s_waitcnt lgkmcnt(4)
	v_mfma_f32_16x16x32_bf16 v[60:63], v[64:67], v[12:15], v[56:59]
	v_mfma_f32_16x16x32_bf16 v[64:67], v[64:67], v[28:31], v[52:55]
	s_setprio 0
	s_nop 3
	ds_read_b128 v[52:55], v175 offset:8704
	ds_read_b128 v[56:59], v175 offset:8768
	ds_read_b128 v[88:91], v175 offset:8832
	ds_read_b128 v[92:95], v175 offset:8896
	s_setprio 1
	s_waitcnt lgkmcnt(7)
	v_mfma_f32_16x16x32_bf16 v[96:99], v[68:71], v[32:35], v[84:87]
	v_mfma_f32_16x16x32_bf16 v[68:71], v[68:71], v[16:19], v[84:87]
	s_waitcnt lgkmcnt(6)
; DEVINL float fexp2(float x) { return __builtin_amdgcn_exp2f(x); }
; #define LDK(DST, KQ) _Pragma("unroll") for (int kc = 0; kc < 4; ++kc) DST[kc] = *(const bf16x8*)(Ks + ((KQ) * 16 + fr) * 136 + kc * 32 + fq * 8)
; DEVINL void attn_item(const Params& p, int item, char* smem, int wv) {
;     ...
;     LDK(kfb, 1); MMS(kfa, 0);
;     LDK(kfa, 2); MMS(kfb, 1);
;     LDK(kfb, 3); MMS(kfa, 2);
;     LDV(vfa, 0); MMS(kfb, 3);
;     bf16x8 pf[2][2];
;     {
;       const unsigned long long msh = mw >> (fq * 4);
;       const int mlo = (int)(unsigned)msh, mhi = (int)(unsigned)(msh >> 32);
;       int mk[4][4];
; #pragma unroll
;       for (int j = 0; j < 4; ++j) {
;         mk[0][j] = __builtin_amdgcn_sbfe(mlo, j, 1); mk[1][j] = __builtin_amdgcn_sbfe(mlo, 16 + j, 1);
;         mk[2][j] = __builtin_amdgcn_sbfe(mhi, j, 1); mk[3][j] = __builtin_amdgcn_sbfe(mhi, 16 + j, 1);
;       }
; #pragma unroll
;       for (int hh = 0; hh < 2; ++hh) {
;         float mx = s[hh][0][0];
; #pragma unroll
;         for (int kq = 0; kq < 4; ++kq)
; #pragma unroll
;           for (int j = 0; j < 4; ++j) mx = fmaxf(mx, s[hh][kq][j]);
;         {
;           auto r1 = __builtin_amdgcn_permlane16_swap(__float_as_uint(mx), __float_as_uint(mx), false, false);
;           mx = fmaxf(__uint_as_float(r1[0]), __uint_as_float(r1[1]));
;           auto r2 = __builtin_amdgcn_permlane32_swap(__float_as_uint(mx), __float_as_uint(mx), false, false);
;           mx = fmaxf(__uint_as_float(r2[0]), __uint_as_float(r2[1]));
;         }
;         if (kt == 0 || __ballot(mx > 8.f)) {
;           const float delta = (kt == 0) ? mx : fmaxf(mx, 0.f);
;           const float alpha = fexp2(-delta);
;           mrun[hh] += delta;
;           lsum[hh] *= alpha;
; #pragma unroll
;           for (int dt = 0; dt < 8; ++dt) o[hh][dt] *= alpha;
; #pragma unroll
;           for (int kq = 0; kq < 4; ++kq)
; #pragma unroll
;             for (int j = 0; j < 4; ++j) s[hh][kq][j] -= delta;
;         }
;         float ps = 0.f;
;         float pv[4][4];
; #pragma unroll
;         for (int kq = 0; kq < 4; ++kq)
; #pragma unroll
;           for (int j = 0; j < 4; ++j) {
;             pv[kq][j] = __uint_as_float(__float_as_uint(fexp2(s[hh][kq][j])) & (unsigned)mk[kq][j]);
;             ps += pv[kq][j];
;           }
	v_mfma_f32_16x16x32_bf16 v[96:99], v[72:75], v[4:7], v[96:99]
	v_mfma_f32_16x16x32_bf16 v[68:71], v[72:75], v[20:23], v[68:71]
	s_waitcnt lgkmcnt(5)
	v_mfma_f32_16x16x32_bf16 v[72:75], v[76:79], v[8:11], v[96:99]
	v_mfma_f32_16x16x32_bf16 v[68:71], v[76:79], v[24:27], v[68:71]
	s_waitcnt lgkmcnt(4)
	v_mfma_f32_16x16x32_bf16 v[72:75], v[80:83], v[12:15], v[72:75]
	v_mfma_f32_16x16x32_bf16 v[68:71], v[80:83], v[28:31], v[68:71]
	s_setprio 0
	ds_read_b128 v[76:79], v175 offset:13056
	ds_read_b128 v[80:83], v175 offset:13120
	ds_read_b128 v[96:99], v175 offset:13184
	ds_read_b128 v[100:103], v175 offset:13248
	s_setprio 1
	s_waitcnt lgkmcnt(7)
	v_mfma_f32_16x16x32_bf16 v[104:107], v[52:55], v[32:35], v[84:87]
	v_mfma_f32_16x16x32_bf16 v[52:55], v[52:55], v[16:19], v[84:87]
	s_waitcnt lgkmcnt(6)
	v_mfma_f32_16x16x32_bf16 v[104:107], v[56:59], v[4:7], v[104:107]
	v_mfma_f32_16x16x32_bf16 v[52:55], v[56:59], v[20:23], v[52:55]
	s_waitcnt lgkmcnt(5)
	v_mfma_f32_16x16x32_bf16 v[56:59], v[88:91], v[8:11], v[104:107]
	v_mfma_f32_16x16x32_bf16 v[52:55], v[88:91], v[24:27], v[52:55]
	s_waitcnt lgkmcnt(4)
	v_mfma_f32_16x16x32_bf16 v[88:91], v[92:95], v[12:15], v[56:59]
	v_mfma_f32_16x16x32_bf16 v[92:95], v[92:95], v[28:31], v[52:55]
	s_setprio 0
	s_nop 2
	s_nop 0
	ds_read_b128 v[52:55], v177 offset:17408
	ds_read_b128 v[56:59], v177 offset:17472
	s_setprio 1
	s_waitcnt lgkmcnt(5)
	v_mfma_f32_16x16x32_bf16 v[104:107], v[76:79], v[32:35], v[84:87]
	v_mfma_f32_16x16x32_bf16 v[76:79], v[76:79], v[16:19], v[84:87]
	s_waitcnt lgkmcnt(4)
	v_mfma_f32_16x16x32_bf16 v[84:87], v[80:83], v[4:7], v[104:107]
	v_mfma_f32_16x16x32_bf16 v[76:79], v[80:83], v[20:23], v[76:79]
	s_waitcnt lgkmcnt(3)
	v_mfma_f32_16x16x32_bf16 v[80:83], v[96:99], v[8:11], v[84:87]
	v_mfma_f32_16x16x32_bf16 v[76:79], v[96:99], v[24:27], v[76:79]
	s_waitcnt lgkmcnt(2)
	v_mfma_f32_16x16x32_bf16 v[80:83], v[100:103], v[12:15], v[80:83]
	v_mfma_f32_16x16x32_bf16 v[76:79], v[100:103], v[28:31], v[76:79]
	s_setprio 0
	s_waitcnt vmcnt(5)
	v_lshrrev_b64 v[2:3], v174, v[2:3]
	v_bfe_i32 v0, v2, 0, 1
	v_bfe_i32 v86, v2, 16, 1
	v_bfe_i32 v87, v3, 0, 1
	v_bfe_i32 v96, v3, 16, 1
	v_bfe_i32 v97, v2, 1, 1
	v_bfe_i32 v98, v2, 17, 1
	v_bfe_i32 v99, v3, 1, 1
	v_bfe_i32 v104, v3, 17, 1
	v_bfe_i32 v100, v2, 2, 1
	v_bfe_i32 v101, v2, 18, 1
	v_bfe_i32 v105, v3, 2, 1
	v_bfe_i32 v106, v3, 18, 1
	v_bfe_i32 v102, v2, 3, 1
	v_bfe_i32 v103, v2, 19, 1
	v_bfe_i32 v107, v3, 3, 1
	v_bfe_i32 v108, v3, 19, 1
	v_max_f32_e32 v3, v60, v60
	v_max_f32_e32 v2, v3, v61
	v_max3_f32 v2, v2, v62, v63
	v_max3_f32 v2, v2, v72, v73
	v_max3_f32 v2, v2, v74, v75
	v_max3_f32 v2, v2, v88, v89
	v_max3_f32 v2, v2, v90, v91
	v_max3_f32 v2, v2, v80, v81
	v_max3_f32 v2, v2, v82, v83
	v_mov_b32_e32 v3, v2
	s_nop 1
	v_permlane16_swap_b32_e32 v2, v3
	v_max_f32_e32 v2, v2, v3
	v_mov_b32_e32 v3, v2
	s_nop 1
	v_permlane32_swap_b32_e32 v2, v3
	v_max_f32_e32 v3, v2, v3
	v_sub_f32_e32 v2, v80, v3
	v_sub_f32_e32 v61, v61, v3
	v_sub_f32_e32 v80, v81, v3
	v_sub_f32_e32 v81, v82, v3
	v_sub_f32_e32 v82, v83, v3
	v_sub_f32_e32 v83, v88, v3
	v_sub_f32_e32 v88, v90, v3
	v_exp_f32_e32 v90, v61
	v_exp_f32_e32 v115, v2
	v_max_f32_e32 v61, v64, v64
	v_max_f32_e32 v2, v61, v65
	v_max3_f32 v2, v2, v66, v67
	v_max3_f32 v2, v2, v68, v69
	v_max3_f32 v2, v2, v70, v71
	v_max3_f32 v2, v2, v92, v93
	v_max3_f32 v2, v2, v94, v95
	v_max3_f32 v2, v2, v76, v77
	v_max3_f32 v2, v2, v78, v79
	v_mov_b32_e32 v61, v2
	s_nop 1
	v_permlane16_swap_b32_e32 v2, v61
	v_max_f32_e32 v2, v2, v61
	v_mov_b32_e32 v61, v2
	s_nop 1
	v_permlane32_swap_b32_e32 v2, v61
	v_max_f32_e32 v2, v2, v61
	v_sub_f32_e32 v60, v60, v3
	v_sub_f32_e32 v64, v64, v2
	v_exp_f32_e32 v60, v60
	v_sub_f32_e32 v65, v65, v2
	v_exp_f32_e32 v64, v64
	v_sub_f32_e32 v62, v62, v3
	v_sub_f32_e32 v66, v66, v2
	v_exp_f32_e32 v65, v65
	v_sub_f32_e32 v85, v89, v3
	v_sub_f32_e32 v89, v91, v3
	v_sub_f32_e32 v63, v63, v3
	v_exp_f32_e32 v91, v62
	v_sub_f32_e32 v67, v67, v2
	v_exp_f32_e32 v66, v66
	v_sub_f32_e32 v72, v72, v3
	v_exp_f32_e32 v109, v63
	v_sub_f32_e32 v61, v68, v2
	v_sub_f32_e32 v62, v69, v2
	v_exp_f32_e32 v67, v67
	v_sub_f32_e32 v73, v73, v3
	v_exp_f32_e32 v72, v72
	v_exp_f32_e32 v113, v83
	v_exp_f32_e32 v125, v82
	v_sub_f32_e32 v82, v92, v2
	v_sub_f32_e32 v83, v93, v2
	v_sub_f32_e32 v63, v70, v2
	v_sub_f32_e32 v68, v71, v2
	v_exp_f32_e32 v70, v61
	v_exp_f32_e32 v71, v62
	v_and_b32_e32 v61, v0, v64
	v_and_b32_e32 v60, v0, v60
	v_and_b32_e32 v62, v97, v90
	v_sub_f32_e32 v74, v74, v3
	v_exp_f32_e32 v110, v73
	v_exp_f32_e32 v121, v80
	v_exp_f32_e32 v124, v81
	v_sub_f32_e32 v122, v76, v2
	v_sub_f32_e32 v126, v78, v2
	v_exp_f32_e32 v76, v63
	v_exp_f32_e32 v78, v68
	v_and_b32_e32 v63, v97, v65
	v_cvt_pk_bf16_f32 v68, v60, v62
	v_pk_add_f32 v[80:81], v[60:61], 0 op_sel_hi:[1,0]
	v_exp_f32_e32 v0, v82
	v_exp_f32_e32 v60, v83
	v_sub_f32_e32 v75, v75, v3
	v_exp_f32_e32 v111, v74
	v_and_b32_e32 v65, v100, v66
	v_and_b32_e32 v64, v100, v91
	v_pk_add_f32 v[80:81], v[80:81], v[62:63]
	v_exp_f32_e32 v112, v75
	v_and_b32_e32 v67, v102, v67
	v_and_b32_e32 v66, v102, v109
	v_pk_add_f32 v[80:81], v[80:81], v[64:65]
	v_sub_f32_e32 v93, v95, v2
	v_and_b32_e32 v73, v86, v70
	v_and_b32_e32 v72, v86, v72
	v_pk_add_f32 v[80:81], v[80:81], v[66:67]
	v_exp_f32_e32 v114, v85
	v_sub_f32_e32 v92, v94, v2
	v_and_b32_e32 v75, v98, v71
	v_and_b32_e32 v74, v98, v110
	v_pk_add_f32 v[80:81], v[80:81], v[72:73]
	v_and_b32_e32 v83, v87, v0
	v_and_b32_e32 v82, v87, v113
	v_and_b32_e32 v87, v99, v60
	v_exp_f32_e32 v60, v93
	v_exp_f32_e32 v88, v88
; DEVINL float fexp2(float x) { return __builtin_amdgcn_exp2f(x); }
; DEVINL uint32_t pk2(float a, float b) { hwf2 v = {a, b}; hwbf2 r = __builtin_convertvector(v, hwbf2); return *(uint32_t*)&r; }
; #define MMV(SRC, DT) do { __builtin_amdgcn_s_setprio(1); _Pragma("unroll") for (int c2 = 0; c2 < 2; ++c2) { o[0][DT] = mfma16(SRC[c2], pf[0][c2], o[0][DT]); o[1][DT] = mfma16(SRC[c2], pf[1][c2], o[1][DT]); } __builtin_amdgcn_s_setprio(0); } while (0)
; DEVINL void attn_item(const Params& p, int item, char* smem, int wv) {
;     ...
;         float ps = 0.f;
;         float pv[4][4];
; #pragma unroll
;         for (int kq = 0; kq < 4; ++kq)
; #pragma unroll
;           for (int j = 0; j < 4; ++j) {
;             pv[kq][j] = __uint_as_float(__float_as_uint(fexp2(s[hh][kq][j])) & (unsigned)mk[kq][j]);
;             ps += pv[kq][j];
;           }
; #pragma unroll
;         for (int c2 = 0; c2 < 2; ++c2) {
;           u32x4 pw;
;           pw[0] = pk2(pv[2 * c2][0], pv[2 * c2][1]); pw[1] = pk2(pv[2 * c2][2], pv[2 * c2][3]);
;           pw[2] = pk2(pv[2 * c2 + 1][0], pv[2 * c2 + 1][1]); pw[3] = pk2(pv[2 * c2 + 1][2], pv[2 * c2 + 1][3]);
;           pf[hh][c2] = *(bf16x8*)&pw;
;         }
;         lsum[hh] += ps;
;       }
;     }
;     LDV(vfb, 1); MMV(vfa, 0);
;     LDV(vfa, 2); MMV(vfb, 1);
;     LDV(vfb, 3); MMV(vfa, 2);
;     LDV(vfa, 4); MMV(vfb, 3);
;     LDV(vfb, 5); MMV(vfa, 4);
;     LDV(vfa, 6); MMV(vfb, 5);
;     LDV(vfb, 7); MMV(vfa, 6);
;     MMV(vfb, 7);
	v_sub_f32_e32 v123, v77, v2
	v_and_b32_e32 v77, v101, v76
	v_and_b32_e32 v76, v101, v111
	v_pk_add_f32 v[80:81], v[80:81], v[74:75]
	v_exp_f32_e32 v0, v92
	v_exp_f32_e32 v89, v89
	v_sub_f32_e32 v127, v79, v2
	v_and_b32_e32 v79, v103, v78
	v_and_b32_e32 v78, v103, v112
	v_pk_add_f32 v[80:81], v[80:81], v[76:77]
	v_exp_f32_e32 v62, v122
	v_pk_add_f32 v[80:81], v[80:81], v[78:79]
	v_cvt_pk_bf16_f32 v69, v64, v66
	v_and_b32_e32 v86, v99, v114
	v_exp_f32_e32 v64, v123
	v_cvt_pk_bf16_f32 v100, v61, v63
	v_cvt_pk_bf16_f32 v102, v73, v75
	v_and_b32_e32 v75, v107, v60
	v_pk_add_f32 v[60:61], v[80:81], v[82:83]
	v_cvt_pk_bf16_f32 v70, v72, v74
	v_exp_f32_e32 v66, v126
	v_and_b32_e32 v73, v105, v0
	v_and_b32_e32 v72, v105, v88
	v_pk_add_f32 v[60:61], v[60:61], v[86:87]
	v_exp_f32_e32 v90, v127
	v_and_b32_e32 v74, v107, v89
	v_pk_add_f32 v[60:61], v[60:61], v[72:73]
	v_cvt_pk_bf16_f32 v71, v76, v78
	v_cvt_pk_bf16_f32 v103, v77, v79
	v_and_b32_e32 v77, v96, v62
	v_and_b32_e32 v76, v96, v115
	v_pk_add_f32 v[60:61], v[60:61], v[74:75]
	v_and_b32_e32 v79, v104, v64
	v_and_b32_e32 v78, v104, v121
	v_pk_add_f32 v[60:61], v[60:61], v[76:77]
	v_and_b32_e32 v89, v106, v66
	v_and_b32_e32 v88, v106, v124
	v_pk_add_f32 v[60:61], v[60:61], v[78:79]
	v_and_b32_e32 v91, v108, v90
	v_and_b32_e32 v90, v108, v125
	v_pk_add_f32 v[60:61], v[60:61], v[88:89]
	v_exp_f32_e64 v84, -v3
	v_exp_f32_e64 v85, -v2
	v_cvt_pk_bf16_f32 v101, v65, v67
	v_pk_add_f32 v[80:81], v[60:61], v[90:91]
	ds_read_b128 v[60:63], v177 offset:19712
	ds_read_b128 v[64:67], v177 offset:19776
	v_pk_add_f32 v[2:3], v[2:3], 0 op_sel_hi:[1,0]
	v_pk_mul_f32 v[122:123], v[84:85], 0 op_sel_hi:[1,0]
	v_pk_fma_f32 v[160:161], v[84:85], 0, v[80:81] op_sel_hi:[1,0,1]
	v_mov_b32_e32 v126, v122
	v_mov_b32_e32 v127, v122
	v_mov_b32_e32 v128, v122
	v_mov_b32_e32 v129, v122
	v_cvt_pk_bf16_f32 v130, v82, v86
	v_cvt_pk_bf16_f32 v131, v72, v74
	v_cvt_pk_bf16_f32 v132, v76, v78
	v_cvt_pk_bf16_f32 v133, v88, v90
	v_mov_b32_e32 v122, v123
	v_mov_b32_e32 v124, v123
	v_mov_b32_e32 v125, v123
	v_cvt_pk_bf16_f32 v134, v83, v87
	v_cvt_pk_bf16_f32 v135, v73, v75
	v_cvt_pk_bf16_f32 v136, v77, v79
	v_cvt_pk_bf16_f32 v137, v89, v91
	s_setprio 1
	s_waitcnt lgkmcnt(3)
	v_mfma_f32_16x16x32_bf16 v[72:75], v[52:55], v[68:71], v[126:129]
	v_mfma_f32_16x16x32_bf16 v[52:55], v[52:55], v[100:103], v[122:125]
	s_waitcnt lgkmcnt(2)
	v_mfma_f32_16x16x32_bf16 v[88:91], v[56:59], v[130:133], v[72:75]
	v_mfma_f32_16x16x32_bf16 v[52:55], v[56:59], v[134:137], v[52:55]
	s_setprio 0
	s_nop 1
	s_nop 0
	ds_read_b128 v[72:75], v177 offset:22016
	ds_read_b128 v[76:79], v177 offset:22080
	s_setprio 1
	s_waitcnt lgkmcnt(3)
	v_mfma_f32_16x16x32_bf16 v[56:59], v[60:63], v[68:71], v[126:129]
	v_mfma_f32_16x16x32_bf16 v[60:63], v[60:63], v[100:103], v[122:125]
	s_waitcnt lgkmcnt(2)
	v_mfma_f32_16x16x32_bf16 v[84:87], v[64:67], v[130:133], v[56:59]
	v_mfma_f32_16x16x32_bf16 v[56:59], v[64:67], v[134:137], v[60:63]
	s_setprio 0
	ds_read_b128 v[64:67], v177 offset:24320
	ds_read_b128 v[80:83], v177 offset:24384
	s_setprio 1
	s_waitcnt lgkmcnt(3)
	v_mfma_f32_16x16x32_bf16 v[60:63], v[72:75], v[68:71], v[126:129]
	v_mfma_f32_16x16x32_bf16 v[72:75], v[72:75], v[100:103], v[122:125]
	s_waitcnt lgkmcnt(2)
	v_mfma_f32_16x16x32_bf16 v[92:95], v[76:79], v[130:133], v[60:63]
	v_mfma_f32_16x16x32_bf16 v[60:63], v[76:79], v[134:137], v[72:75]
	s_setprio 0
	s_nop 2
	s_nop 0
	ds_read_b128 v[72:75], v177 offset:26624
	ds_read_b128 v[76:79], v177 offset:26688
	s_setprio 1
	s_waitcnt lgkmcnt(3)
	v_mfma_f32_16x16x32_bf16 v[96:99], v[64:67], v[68:71], v[126:129]
	v_mfma_f32_16x16x32_bf16 v[64:67], v[64:67], v[100:103], v[122:125]
	s_waitcnt lgkmcnt(2)
	v_mfma_f32_16x16x32_bf16 v[96:99], v[80:83], v[130:133], v[96:99]
	v_mfma_f32_16x16x32_bf16 v[64:67], v[80:83], v[134:137], v[64:67]
	s_setprio 0
	ds_read_b128 v[80:83], v177 offset:28928
	ds_read_b128 v[112:115], v177 offset:28992
	s_setprio 1
	s_waitcnt lgkmcnt(3)
	v_mfma_f32_16x16x32_bf16 v[104:107], v[72:75], v[68:71], v[126:129]
	v_mfma_f32_16x16x32_bf16 v[72:75], v[72:75], v[100:103], v[122:125]
	s_waitcnt lgkmcnt(2)
	v_mfma_f32_16x16x32_bf16 v[104:107], v[76:79], v[130:133], v[104:107]
	v_mfma_f32_16x16x32_bf16 v[72:75], v[76:79], v[134:137], v[72:75]
	s_setprio 0
	ds_read_b128 v[138:141], v177 offset:31232
	ds_read_b128 v[142:145], v177 offset:31296
	s_setprio 1
	s_waitcnt lgkmcnt(3)
	v_mfma_f32_16x16x32_bf16 v[76:79], v[80:83], v[68:71], v[126:129]
	v_mfma_f32_16x16x32_bf16 v[80:83], v[80:83], v[100:103], v[122:125]
	s_waitcnt lgkmcnt(2)
	v_mfma_f32_16x16x32_bf16 v[108:111], v[112:115], v[130:133], v[76:79]
	v_mfma_f32_16x16x32_bf16 v[76:79], v[112:115], v[134:137], v[80:83]
	s_setprio 0
	ds_read_b128 v[146:149], v177 offset:33536
	ds_read_b128 v[150:153], v177 offset:33600
	s_setprio 1
	s_waitcnt lgkmcnt(3)
	v_mfma_f32_16x16x32_bf16 v[80:83], v[138:141], v[68:71], v[126:129]
	v_mfma_f32_16x16x32_bf16 v[138:141], v[138:141], v[100:103], v[122:125]
	s_waitcnt lgkmcnt(2)
	v_mfma_f32_16x16x32_bf16 v[112:115], v[142:145], v[130:133], v[80:83]
	v_mfma_f32_16x16x32_bf16 v[80:83], v[142:145], v[134:137], v[138:141]
	s_setprio 0
	s_setprio 1
	s_waitcnt lgkmcnt(1)
	v_mfma_f32_16x16x32_bf16 v[68:71], v[146:149], v[68:71], v[126:129]
	v_mfma_f32_16x16x32_bf16 v[122:125], v[146:149], v[100:103], v[122:125]
	s_waitcnt lgkmcnt(0)
	v_mfma_f32_16x16x32_bf16 v[100:103], v[150:153], v[130:133], v[68:71]
	v_mfma_f32_16x16x32_bf16 v[68:71], v[150:153], v[134:137], v[122:125]
	s_setprio 0
	s_cbranch_execz .LBB0_705
	s_branch .LBB0_706

; DEVINL float fexp2(float x) { return __builtin_amdgcn_exp2f(x); }
; #define LDK(DST, KQ) _Pragma("unroll") for (int kc = 0; kc < 4; ++kc) DST[kc] = *(const bf16x8*)(Ks + ((KQ) * 16 + fr) * 136 + kc * 32 + fq * 8)
; DEVINL void attn_item(const Params& p, int item, char* smem, int wv) {
;     ...
;     if (kt * 64 <= qlast) {
;     f32x4 s[2][4];
;     bf16x8 kfa[4], kfb[4];
;     bf16x8 vfa[2], vfb[2];
;     ...
;     LDK(kfa, 0);
;     LDK(kfb, 1); MMS(kfa, 0);
;     LDK(kfa, 2); MMS(kfb, 1);
;     LDK(kfb, 3); MMS(kfa, 2);
;     LDV(vfa, 0); MMS(kfb, 3);
;     bf16x8 pf[2][2];
;     {
;       const unsigned long long msh = mw >> (fq * 4);
;       const int mlo = (int)(unsigned)msh, mhi = (int)(unsigned)(msh >> 32);
;       int mk[4][4];
; #pragma unroll
;       for (int j = 0; j < 4; ++j) {
;         mk[0][j] = __builtin_amdgcn_sbfe(mlo, j, 1); mk[1][j] = __builtin_amdgcn_sbfe(mlo, 16 + j, 1);
;         mk[2][j] = __builtin_amdgcn_sbfe(mhi, j, 1); mk[3][j] = __builtin_amdgcn_sbfe(mhi, 16 + j, 1);
;       }
; #pragma unroll
;       for (int hh = 0; hh < 2; ++hh) {
;         float mx = s[hh][0][0];
; #pragma unroll
;         for (int kq = 0; kq < 4; ++kq)
; #pragma unroll
;           for (int j = 0; j < 4; ++j) mx = fmaxf(mx, s[hh][kq][j]);
;         {
;           auto r1 = __builtin_amdgcn_permlane16_swap(__float_as_uint(mx), __float_as_uint(mx), false, false);
;           mx = fmaxf(__uint_as_float(r1[0]), __uint_as_float(r1[1]));
;           auto r2 = __builtin_amdgcn_permlane32_swap(__float_as_uint(mx), __float_as_uint(mx), false, false);
;           mx = fmaxf(__uint_as_float(r2[0]), __uint_as_float(r2[1]));
;         }
;         if (kt == 0 || __ballot(mx > 8.f)) {
;           const float delta = (kt == 0) ? mx : fmaxf(mx, 0.f);
;           const float alpha = fexp2(-delta);
;           mrun[hh] += delta;
;           lsum[hh] *= alpha;
; #pragma unroll
;           for (int dt = 0; dt < 8; ++dt) o[hh][dt] *= alpha;
; #pragma unroll
;           for (int kq = 0; kq < 4; ++kq)
; #pragma unroll
;             for (int j = 0; j < 4; ++j) s[hh][kq][j] -= delta;
;         }
.LBB0_709:
	s_add_i32 s8, s6, 0xffffffa0
	s_cmp_gt_i32 s8, s1
	s_cbranch_scc1 .LBB0_715
	ds_read_b128 v[116:119], v175
	ds_read_b128 v[120:123], v175 offset:64
	ds_read_b128 v[124:127], v175 offset:128
	ds_read_b128 v[128:131], v175 offset:192
	ds_read_b128 v[132:135], v175 offset:4352
	ds_read_b128 v[140:143], v175 offset:4416
	ds_read_b128 v[144:147], v175 offset:4480
	ds_read_b128 v[178:181], v175 offset:4544
	v_xor_b32_e32 v182, 0x80000000, v3
	v_xor_b32_e32 v186, 0x80000000, v2
	v_mov_b32_e32 v183, v182
	v_mov_b32_e32 v184, v182
	v_mov_b32_e32 v185, v182
	v_mov_b32_e32 v187, v186
	v_mov_b32_e32 v188, v186
	v_mov_b32_e32 v189, v186
	s_setprio 1
	s_waitcnt lgkmcnt(7)
	v_mfma_f32_16x16x32_bf16 v[136:139], v[116:119], v[32:35], v[182:185]
	v_mfma_f32_16x16x32_bf16 v[116:119], v[116:119], v[16:19], v[186:189]
	s_waitcnt lgkmcnt(6)
	v_mfma_f32_16x16x32_bf16 v[136:139], v[120:123], v[4:7], v[136:139]
	v_mfma_f32_16x16x32_bf16 v[116:119], v[120:123], v[20:23], v[116:119]
	s_waitcnt lgkmcnt(5)
	v_mfma_f32_16x16x32_bf16 v[120:123], v[124:127], v[8:11], v[136:139]
	v_mfma_f32_16x16x32_bf16 v[116:119], v[124:127], v[24:27], v[116:119]
	s_waitcnt lgkmcnt(4)
	v_mfma_f32_16x16x32_bf16 v[152:155], v[128:131], v[12:15], v[120:123]
	v_mfma_f32_16x16x32_bf16 v[136:139], v[128:131], v[28:31], v[116:119]
	s_setprio 0
	s_nop 3
	ds_read_b128 v[116:119], v175 offset:8704
	ds_read_b128 v[120:123], v175 offset:8768
	ds_read_b128 v[124:127], v175 offset:8832
	ds_read_b128 v[128:131], v175 offset:8896
	s_setprio 1
	s_waitcnt lgkmcnt(7)
	v_mfma_f32_16x16x32_bf16 v[148:151], v[132:135], v[32:35], v[182:185]
	v_mfma_f32_16x16x32_bf16 v[132:135], v[132:135], v[16:19], v[186:189]
	s_waitcnt lgkmcnt(6)
	v_mfma_f32_16x16x32_bf16 v[148:151], v[140:143], v[4:7], v[148:151]
	v_mfma_f32_16x16x32_bf16 v[132:135], v[140:143], v[20:23], v[132:135]
	s_waitcnt lgkmcnt(5)
	v_mfma_f32_16x16x32_bf16 v[140:143], v[144:147], v[8:11], v[148:151]
	v_mfma_f32_16x16x32_bf16 v[132:135], v[144:147], v[24:27], v[132:135]
	s_waitcnt lgkmcnt(4)
	v_mfma_f32_16x16x32_bf16 v[148:151], v[178:181], v[12:15], v[140:143]
	v_mfma_f32_16x16x32_bf16 v[132:135], v[178:181], v[28:31], v[132:135]
	s_setprio 0
	ds_read_b128 v[144:147], v175 offset:13056
	ds_read_b128 v[178:181], v175 offset:13120
	ds_read_b128 v[190:193], v175 offset:13184
	ds_read_b128 v[194:197], v175 offset:13248
	s_setprio 1
	s_waitcnt lgkmcnt(7)
	v_mfma_f32_16x16x32_bf16 v[140:143], v[116:119], v[32:35], v[182:185]
	v_mfma_f32_16x16x32_bf16 v[116:119], v[116:119], v[16:19], v[186:189]
	s_waitcnt lgkmcnt(6)
	v_mfma_f32_16x16x32_bf16 v[140:143], v[120:123], v[4:7], v[140:143]
	v_mfma_f32_16x16x32_bf16 v[116:119], v[120:123], v[20:23], v[116:119]
	s_waitcnt lgkmcnt(5)
	v_mfma_f32_16x16x32_bf16 v[120:123], v[124:127], v[8:11], v[140:143]
	v_mfma_f32_16x16x32_bf16 v[116:119], v[124:127], v[24:27], v[116:119]
	s_waitcnt lgkmcnt(4)
	v_mfma_f32_16x16x32_bf16 v[140:143], v[128:131], v[12:15], v[120:123]
	v_mfma_f32_16x16x32_bf16 v[124:127], v[128:131], v[28:31], v[116:119]
	s_setprio 0
	s_nop 2
	s_nop 0
	ds_read_b128 v[116:119], v177 offset:17408
	ds_read_b128 v[120:123], v177 offset:17472
	s_setprio 1
	s_waitcnt lgkmcnt(5)
	v_mfma_f32_16x16x32_bf16 v[128:131], v[144:147], v[32:35], v[182:185]
	v_mfma_f32_16x16x32_bf16 v[144:147], v[144:147], v[16:19], v[186:189]
	s_waitcnt lgkmcnt(4)
	v_mfma_f32_16x16x32_bf16 v[128:131], v[178:181], v[4:7], v[128:131]
	v_mfma_f32_16x16x32_bf16 v[144:147], v[178:181], v[20:23], v[144:147]
	s_waitcnt lgkmcnt(3)
	v_mfma_f32_16x16x32_bf16 v[128:131], v[190:193], v[8:11], v[128:131]
	v_mfma_f32_16x16x32_bf16 v[178:181], v[190:193], v[24:27], v[144:147]
	s_waitcnt lgkmcnt(2)
	v_mfma_f32_16x16x32_bf16 v[144:147], v[194:197], v[12:15], v[128:131]
	v_mfma_f32_16x16x32_bf16 v[128:131], v[194:197], v[28:31], v[178:181]
	s_setprio 0
	s_nop 3
	v_max_f32_e32 v179, v152, v152
	v_max_f32_e32 v178, v179, v153
	v_max3_f32 v178, v178, v154, v155
	v_max3_f32 v178, v178, v148, v149
	v_max3_f32 v178, v178, v150, v151
	v_max3_f32 v178, v178, v140, v141
	v_max3_f32 v178, v178, v142, v143
	v_max3_f32 v178, v178, v144, v145
	v_max3_f32 v178, v178, v146, v147
	v_mov_b32_e32 v179, v178
	s_nop 1
	v_permlane16_swap_b32_e32 v178, v179
	v_max_f32_e32 v178, v178, v179
	v_mov_b32_e32 v179, v178
	s_nop 1
	v_permlane32_swap_b32_e32 v178, v179
	v_max_f32_e32 v178, v178, v179
	v_cmp_lt_f32_e32 vcc, s25, v178
	s_cbranch_vccz .LBB0_712
	v_max_f32_e32 v178, 0, v178
	v_exp_f32_e64 v180, -v178
	v_add_f32_e32 v3, v3, v178
	v_pk_add_f32 v[152:153], v[152:153], v[178:179] op_sel_hi:[1,0] neg_lo:[0,1] neg_hi:[0,1]
	v_pk_add_f32 v[154:155], v[154:155], v[178:179] op_sel_hi:[1,0] neg_lo:[0,1] neg_hi:[0,1]
	v_mul_f32_e32 v160, v160, v180
	v_pk_mul_f32 v[90:91], v[90:91], v[180:181] op_sel_hi:[1,0]
	v_pk_mul_f32 v[88:89], v[88:89], v[180:181] op_sel_hi:[1,0]
	v_pk_mul_f32 v[86:87], v[86:87], v[180:181] op_sel_hi:[1,0]
	v_pk_mul_f32 v[84:85], v[84:85], v[180:181] op_sel_hi:[1,0]
	v_pk_mul_f32 v[94:95], v[94:95], v[180:181] op_sel_hi:[1,0]
	v_pk_mul_f32 v[92:93], v[92:93], v[180:181] op_sel_hi:[1,0]
	v_pk_mul_f32 v[98:99], v[98:99], v[180:181] op_sel_hi:[1,0]
	v_pk_mul_f32 v[96:97], v[96:97], v[180:181] op_sel_hi:[1,0]
	v_pk_mul_f32 v[106:107], v[106:107], v[180:181] op_sel_hi:[1,0]
	v_pk_mul_f32 v[104:105], v[104:105], v[180:181] op_sel_hi:[1,0]
	v_pk_mul_f32 v[110:111], v[110:111], v[180:181] op_sel_hi:[1,0]
	v_pk_mul_f32 v[108:109], v[108:109], v[180:181] op_sel_hi:[1,0]
	v_pk_mul_f32 v[114:115], v[114:115], v[180:181] op_sel_hi:[1,0]
	v_pk_mul_f32 v[112:113], v[112:113], v[180:181] op_sel_hi:[1,0]
	v_pk_mul_f32 v[102:103], v[102:103], v[180:181] op_sel_hi:[1,0]
	v_pk_mul_f32 v[100:101], v[100:101], v[180:181] op_sel_hi:[1,0]
	v_pk_add_f32 v[148:149], v[148:149], v[178:179] op_sel_hi:[1,0] neg_lo:[0,1] neg_hi:[0,1]
	v_pk_add_f32 v[150:151], v[150:151], v[178:179] op_sel_hi:[1,0] neg_lo:[0,1] neg_hi:[0,1]
	v_pk_add_f32 v[140:141], v[140:141], v[178:179] op_sel_hi:[1,0] neg_lo:[0,1] neg_hi:[0,1]
	v_pk_add_f32 v[142:143], v[142:143], v[178:179] op_sel_hi:[1,0] neg_lo:[0,1] neg_hi:[0,1]
	v_pk_add_f32 v[144:145], v[144:145], v[178:179] op_sel_hi:[1,0] neg_lo:[0,1] neg_hi:[0,1]
	v_pk_add_f32 v[146:147], v[146:147], v[178:179] op_sel_hi:[1,0] neg_lo:[0,1] neg_hi:[0,1]

; DEVINL float fexp2(float x) { return __builtin_amdgcn_exp2f(x); }
; DEVINL void attn_item(const Params& p, int item, char* smem, int wv) {
;     ...
;       const unsigned long long msh = mw >> (fq * 4);
;       const int mlo = (int)(unsigned)msh, mhi = (int)(unsigned)(msh >> 32);
;       int mk[4][4];
; #pragma unroll
;       for (int j = 0; j < 4; ++j) {
;         mk[0][j] = __builtin_amdgcn_sbfe(mlo, j, 1); mk[1][j] = __builtin_amdgcn_sbfe(mlo, 16 + j, 1);
;         mk[2][j] = __builtin_amdgcn_sbfe(mhi, j, 1); mk[3][j] = __builtin_amdgcn_sbfe(mhi, 16 + j, 1);
;       }
; #pragma unroll
;       for (int hh = 0; hh < 2; ++hh) {
;         float mx = s[hh][0][0];
; #pragma unroll
;         for (int kq = 0; kq < 4; ++kq)
; #pragma unroll
;           for (int j = 0; j < 4; ++j) mx = fmaxf(mx, s[hh][kq][j]);
;         {
;           auto r1 = __builtin_amdgcn_permlane16_swap(__float_as_uint(mx), __float_as_uint(mx), false, false);
;           mx = fmaxf(__uint_as_float(r1[0]), __uint_as_float(r1[1]));
;           auto r2 = __builtin_amdgcn_permlane32_swap(__float_as_uint(mx), __float_as_uint(mx), false, false);
;           mx = fmaxf(__uint_as_float(r2[0]), __uint_as_float(r2[1]));
;         }
;         if (kt == 0 || __ballot(mx > 8.f)) {
;           const float delta = (kt == 0) ? mx : fmaxf(mx, 0.f);
;           const float alpha = fexp2(-delta);
;           mrun[hh] += delta;
;           lsum[hh] *= alpha;
; #pragma unroll
;           for (int dt = 0; dt < 8; ++dt) o[hh][dt] *= alpha;
; #pragma unroll
;           for (int kq = 0; kq < 4; ++kq)
; #pragma unroll
;             for (int j = 0; j < 4; ++j) s[hh][kq][j] -= delta;
;         }
;         float ps = 0.f;
;         float pv[4][4];
; #pragma unroll
;         for (int kq = 0; kq < 4; ++kq)
; #pragma unroll
;           for (int j = 0; j < 4; ++j) {
;             pv[kq][j] = __uint_as_float(__float_as_uint(fexp2(s[hh][kq][j])) & (unsigned)mk[kq][j]);
;             ps += pv[kq][j];
;           }
; #pragma unroll
;         for (int c2 = 0; c2 < 2; ++c2) {
;           u32x4 pw;
;           pw[0] = pk2(pv[2 * c2][0], pv[2 * c2][1]); pw[1] = pk2(pv[2 * c2][2], pv[2 * c2][3]);
;           pw[2] = pk2(pv[2 * c2 + 1][0], pv[2 * c2 + 1][1]); pw[3] = pk2(pv[2 * c2 + 1][2], pv[2 * c2 + 1][3]);
;           pf[hh][c2] = *(bf16x8*)&pw;
;         }
;         lsum[hh] += ps;
.LBB0_714:
	v_exp_f32_e32 v152, v152
	v_exp_f32_e32 v153, v153
	v_lshrrev_b64 v[162:163], v174, v[162:163]
	v_exp_f32_e32 v154, v154
	v_bfe_i32 v178, v162, 0, 1
	v_exp_f32_e32 v155, v155
	v_bfe_i32 v180, v162, 1, 1
	v_and_b32_e32 v152, v178, v152
	v_exp_f32_e32 v148, v148
	v_bfe_i32 v187, v162, 2, 1
	v_and_b32_e32 v153, v180, v153
	v_add_f32_e32 v192, 0, v152
	v_exp_f32_e32 v149, v149
	v_bfe_i32 v186, v162, 3, 1
	v_add_f32_e32 v192, v192, v153
	v_and_b32_e32 v154, v187, v154
	v_exp_f32_e32 v150, v150
	v_exp_f32_e32 v141, v141
	v_bfe_i32 v182, v162, 16, 1
	v_and_b32_e32 v155, v186, v155
	v_add_f32_e32 v192, v192, v154
	v_exp_f32_e32 v151, v151
	v_exp_f32_e32 v140, v140
	v_bfe_i32 v181, v162, 17, 1
	v_add_f32_e32 v192, v192, v155
	v_and_b32_e32 v148, v182, v148
	v_bfe_i32 v183, v163, 1, 1
	v_bfe_i32 v188, v162, 19, 1
	v_bfe_i32 v162, v162, 18, 1
	v_and_b32_e32 v149, v181, v149
	v_add_f32_e32 v192, v192, v148
	v_bfe_i32 v179, v163, 0, 1
	v_add_f32_e32 v192, v192, v149
	v_and_b32_e32 v150, v162, v150
	v_and_b32_e32 v193, v183, v141
	v_exp_f32_e32 v141, v142
	v_and_b32_e32 v151, v188, v151
	v_add_f32_e32 v192, v192, v150
	v_and_b32_e32 v194, v179, v140
	v_exp_f32_e32 v140, v143
	v_add_f32_e32 v192, v192, v151
	v_bfe_i32 v190, v163, 2, 1
	v_add_f32_e32 v142, v192, v194
	v_bfe_i32 v189, v163, 3, 1
	v_add_f32_e32 v142, v142, v193
	v_and_b32_e32 v195, v190, v141
	v_and_b32_e32 v192, v189, v140
	v_add_f32_e32 v140, v142, v195
	v_exp_f32_e32 v141, v144
	v_add_f32_e32 v196, v140, v192
	v_exp_f32_e32 v140, v145
	v_exp_f32_e32 v142, v147
	v_exp_f32_e32 v143, v146
	v_bfe_i32 v185, v163, 16, 1
	v_bfe_i32 v184, v163, 17, 1
	v_bfe_i32 v191, v163, 19, 1
	v_and_b32_e32 v198, v185, v141
	v_exp_f32_e32 v136, v136
	v_bfe_i32 v163, v163, 18, 1
	v_and_b32_e32 v197, v184, v140
	v_and_b32_e32 v199, v191, v142
	v_cvt_pk_bf16_f32 v142, v148, v149
	v_add_f32_e32 v148, v196, v198
	v_exp_f32_e32 v137, v137
	v_and_b32_e32 v200, v163, v143
	v_add_f32_e32 v148, v148, v197
	v_exp_f32_e32 v138, v138
	v_add_f32_e32 v148, v148, v200
	v_exp_f32_e32 v139, v139
	v_add_f32_e32 v148, v148, v199
	v_and_b32_e32 v136, v178, v136
	v_exp_f32_e32 v132, v132
	v_add_f32_e32 v160, v160, v148
	v_and_b32_e32 v137, v180, v137
	v_add_f32_e32 v148, 0, v136
	v_exp_f32_e32 v133, v133
	v_add_f32_e32 v148, v148, v137
	v_and_b32_e32 v138, v187, v138
	v_exp_f32_e32 v134, v134
	v_exp_f32_e32 v125, v125
	v_and_b32_e32 v139, v186, v139
	v_add_f32_e32 v148, v148, v138
	v_exp_f32_e32 v135, v135
	v_exp_f32_e32 v124, v124
	v_add_f32_e32 v148, v148, v139
	v_and_b32_e32 v132, v182, v132
	v_and_b32_e32 v133, v181, v133
	v_add_f32_e32 v148, v148, v132
	v_add_f32_e32 v148, v148, v133
	v_and_b32_e32 v134, v162, v134
	v_and_b32_e32 v149, v183, v125
	v_exp_f32_e32 v125, v126
	v_cvt_pk_bf16_f32 v143, v150, v151
	v_and_b32_e32 v135, v188, v135
	v_add_f32_e32 v148, v148, v134
	v_and_b32_e32 v150, v179, v124
	v_exp_f32_e32 v124, v127
	v_add_f32_e32 v148, v148, v135
	v_add_f32_e32 v126, v148, v150
	v_add_f32_e32 v126, v126, v149
	v_and_b32_e32 v151, v190, v125
	v_and_b32_e32 v148, v189, v124
	v_add_f32_e32 v124, v126, v151
	v_cvt_pk_bf16_f32 v140, v152, v153
	v_add_f32_e32 v152, v124, v148
	v_exp_f32_e32 v124, v129
	v_exp_f32_e32 v125, v128
	v_exp_f32_e32 v126, v131
	v_exp_f32_e32 v127, v130
	v_cvt_pk_bf16_f32 v141, v154, v155
	v_and_b32_e32 v153, v184, v124
	v_and_b32_e32 v154, v185, v125
	v_cvt_pk_bf16_f32 v124, v136, v137
	v_and_b32_e32 v155, v191, v126
	v_and_b32_e32 v162, v163, v127
	v_cvt_pk_bf16_f32 v125, v138, v139
	v_cvt_pk_bf16_f32 v126, v132, v133
	v_cvt_pk_bf16_f32 v127, v134, v135
	v_cvt_pk_bf16_f32 v129, v151, v148
	v_add_f32_e32 v148, v152, v154
	ds_read_b128 v[132:135], v177 offset:19712
	ds_read_b128 v[136:139], v177 offset:19776
	v_add_f32_e32 v148, v148, v153
	v_add_f32_e32 v148, v148, v162
	v_add_f32_e32 v148, v148, v155
	v_add_f32_e32 v161, v161, v148
	v_cvt_pk_bf16_f32 v144, v194, v193
	v_cvt_pk_bf16_f32 v145, v195, v192
	v_cvt_pk_bf16_f32 v146, v198, v197
	v_cvt_pk_bf16_f32 v147, v200, v199
	v_cvt_pk_bf16_f32 v128, v150, v149
	v_cvt_pk_bf16_f32 v130, v154, v153
	v_cvt_pk_bf16_f32 v131, v162, v155
	s_setprio 1
	s_waitcnt lgkmcnt(3)
; #define MMV(SRC, DT) do { __builtin_amdgcn_s_setprio(1); _Pragma("unroll") for (int c2 = 0; c2 < 2; ++c2) { o[0][DT] = mfma16(SRC[c2], pf[0][c2], o[0][DT]); o[1][DT] = mfma16(SRC[c2], pf[1][c2], o[1][DT]); } __builtin_amdgcn_s_setprio(0); } while (0)
; DEVINL void attn_item(const Params& p, int item, char* smem, int wv) {
;     ...
;     LDV(vfb, 1); MMV(vfa, 0);
;     LDV(vfa, 2); MMV(vfb, 1);
;     LDV(vfb, 3); MMV(vfa, 2);
;     LDV(vfa, 4); MMV(vfb, 3);
;     LDV(vfb, 5); MMV(vfa, 4);
;     LDV(vfa, 6); MMV(vfb, 5);
;     LDV(vfb, 7); MMV(vfa, 6);
;     MMV(vfb, 7);
	v_mfma_f32_16x16x32_bf16 v[88:91], v[116:119], v[140:143], v[88:91]
	v_mfma_f32_16x16x32_bf16 v[52:55], v[116:119], v[124:127], v[52:55]
	s_waitcnt lgkmcnt(2)
	v_mfma_f32_16x16x32_bf16 v[88:91], v[120:123], v[144:147], v[88:91]
	v_mfma_f32_16x16x32_bf16 v[52:55], v[120:123], v[128:131], v[52:55]
	s_setprio 0
	ds_read_b128 v[116:119], v177 offset:22016
	ds_read_b128 v[120:123], v177 offset:22080
	s_setprio 1
	s_waitcnt lgkmcnt(3)
	v_mfma_f32_16x16x32_bf16 v[84:87], v[132:135], v[140:143], v[84:87]
	v_mfma_f32_16x16x32_bf16 v[56:59], v[132:135], v[124:127], v[56:59]
	s_waitcnt lgkmcnt(2)
	v_mfma_f32_16x16x32_bf16 v[84:87], v[136:139], v[144:147], v[84:87]
	v_mfma_f32_16x16x32_bf16 v[56:59], v[136:139], v[128:131], v[56:59]
	s_setprio 0
	ds_read_b128 v[132:135], v177 offset:24320
	ds_read_b128 v[136:139], v177 offset:24384
	s_setprio 1
	s_waitcnt lgkmcnt(3)
	v_mfma_f32_16x16x32_bf16 v[92:95], v[116:119], v[140:143], v[92:95]
	v_mfma_f32_16x16x32_bf16 v[60:63], v[116:119], v[124:127], v[60:63]
	s_waitcnt lgkmcnt(2)
	v_mfma_f32_16x16x32_bf16 v[92:95], v[120:123], v[144:147], v[92:95]
	v_mfma_f32_16x16x32_bf16 v[60:63], v[120:123], v[128:131], v[60:63]
	s_setprio 0
	ds_read_b128 v[116:119], v177 offset:26624
	ds_read_b128 v[120:123], v177 offset:26688
	s_setprio 1
	s_waitcnt lgkmcnt(3)
	v_mfma_f32_16x16x32_bf16 v[96:99], v[132:135], v[140:143], v[96:99]
	v_mfma_f32_16x16x32_bf16 v[64:67], v[132:135], v[124:127], v[64:67]
	s_waitcnt lgkmcnt(2)
	v_mfma_f32_16x16x32_bf16 v[96:99], v[136:139], v[144:147], v[96:99]
	v_mfma_f32_16x16x32_bf16 v[64:67], v[136:139], v[128:131], v[64:67]
	s_setprio 0
	ds_read_b128 v[132:135], v177 offset:28928
	ds_read_b128 v[136:139], v177 offset:28992
	s_setprio 1
	s_waitcnt lgkmcnt(3)
	v_mfma_f32_16x16x32_bf16 v[104:107], v[116:119], v[140:143], v[104:107]
	v_mfma_f32_16x16x32_bf16 v[72:75], v[116:119], v[124:127], v[72:75]
	s_waitcnt lgkmcnt(2)
	v_mfma_f32_16x16x32_bf16 v[104:107], v[120:123], v[144:147], v[104:107]
	v_mfma_f32_16x16x32_bf16 v[72:75], v[120:123], v[128:131], v[72:75]
	s_setprio 0
	ds_read_b128 v[116:119], v177 offset:31232
	ds_read_b128 v[120:123], v177 offset:31296
	s_setprio 1
	s_waitcnt lgkmcnt(3)
	v_mfma_f32_16x16x32_bf16 v[108:111], v[132:135], v[140:143], v[108:111]
	v_mfma_f32_16x16x32_bf16 v[76:79], v[132:135], v[124:127], v[76:79]
	s_waitcnt lgkmcnt(2)
	v_mfma_f32_16x16x32_bf16 v[108:111], v[136:139], v[144:147], v[108:111]
	v_mfma_f32_16x16x32_bf16 v[76:79], v[136:139], v[128:131], v[76:79]
	s_setprio 0
	ds_read_b128 v[132:135], v177 offset:33536
	ds_read_b128 v[136:139], v177 offset:33600
	s_setprio 1
	s_waitcnt lgkmcnt(3)
	v_mfma_f32_16x16x32_bf16 v[112:115], v[116:119], v[140:143], v[112:115]
	v_mfma_f32_16x16x32_bf16 v[80:83], v[116:119], v[124:127], v[80:83]
	s_waitcnt lgkmcnt(2)
	v_mfma_f32_16x16x32_bf16 v[112:115], v[120:123], v[144:147], v[112:115]
	v_mfma_f32_16x16x32_bf16 v[80:83], v[120:123], v[128:131], v[80:83]
	s_setprio 0
	s_setprio 1
	s_waitcnt lgkmcnt(1)
	v_mfma_f32_16x16x32_bf16 v[100:103], v[132:135], v[140:143], v[100:103]
	v_mfma_f32_16x16x32_bf16 v[68:71], v[132:135], v[124:127], v[68:71]
	s_waitcnt lgkmcnt(0)
	v_mfma_f32_16x16x32_bf16 v[100:103], v[136:139], v[144:147], v[100:103]
	v_mfma_f32_16x16x32_bf16 v[68:71], v[136:139], v[128:131], v[68:71]
	s_setprio 0

; #define LDK(DST, KQ) _Pragma("unroll") for (int kc = 0; kc < 4; ++kc) DST[kc] = *(const bf16x8*)(Ks + ((KQ) * 16 + fr) * 136 + kc * 32 + fq * 8)
; DEVINL void attn_item(const Params& p, int item, char* smem, int wv) {
;     ...
;   const size_t qtok = (size_t)b * SEQ + q0 + wid * 16 + fr;
;   bf16x8 qf[2][4];
; #pragma unroll
;   for (int hh = 0; hh < 2; ++hh)
; #pragma unroll
;     for (int kc = 0; kc < 4; ++kc)
;       qf[hh][kc] = *(const bf16x8*)(hb + qtok * HS + 2560 + (kvh * 2 + hh) * 128 + kc * 32 + fq * 8);
;   f32x4 o[2][8];
; #pragma unroll
;   for (int hh = 0; hh < 2; ++hh)
; #pragma unroll
;     for (int dt = 0; dt < 8; ++dt) o[hh][dt] = f32x4{0.f, 0.f, 0.f, 0.f};
;   float mrun[2] = {0.f, 0.f}, lsum[2] = {0.f, 0.f};
;   unsigned long long mw_next = bits[qtok * 64];
;   u32x4 rk[2], rv[2];
;   const u16* kg = hb + ((size_t)b * SEQ + (tid >> 4)) * HS + 3584 + kvh * 128 + (tid & 15) * 8;
;   const u16* vg = vT + ((size_t)(b * 4 + kvh) * 128 + (tid >> 3)) * SEQ + (tid & 7) * 8;
; #pragma unroll
;   for (int i = 0; i < 2; ++i) {
;     rk[i] = *(const u32x4*)(kg + (size_t)(32 * i) * HS);
;     rv[i] = *(const u32x4*)(vg + (size_t)(64 * i) * SEQ);
;   }
;   for (int kt = 0; kt < ntile; ++kt) {
; #pragma unroll
;     for (int i = 0; i < 2; ++i) {
;       *(u32x4*)(Ks + ((tid >> 4) + 32 * i) * 136 + (tid & 15) * 8) = rk[i];
;       *(u32x4*)(Vs + ((tid >> 3) + 64 * i) * 72 + (tid & 7) * 8) = rv[i];
;     }
;     __syncthreads();
;     if (kt + 1 < ntile) {
; #pragma unroll
;       for (int i = 0; i < 2; ++i) {
;         rk[i] = *(const u32x4*)(kg + (size_t)((kt + 1) * 64 + 32 * i) * HS);
;         rv[i] = *(const u32x4*)(vg + (size_t)(64 * i) * SEQ + (kt + 1) * 64);
;       }
;     }
;     const unsigned long long mw = mw_next;
;     if (kt + 1 < ntile) mw_next = bits[qtok * 64 + kt + 1];
;     if (kt * 64 <= qlast) {
;     f32x4 s[2][4];
;     bf16x8 kfa[4], kfb[4];
;     bf16x8 vfa[2], vfb[2];
;     ...
;     LDK(kfa, 0);
;     LDK(kfb, 1); MMS(kfa, 0);
;     LDK(kfa, 2); MMS(kfb, 1);
; DEVINL void phase_mix(const Params& p, int layer, char* smem, int wv, int rep) {
;     ...
;     for (;;) {
;       int it = next_item(ctr2, smem, wv);
;       if (it >= 512) break;
;       attn_item(p, it, smem, wv);
.LBB0_1723:
	s_or_b64 exec, exec, s[2:3]
	s_waitcnt lgkmcnt(0)
	s_barrier
	ds_read_b32 v0, v170
	s_mov_b64 s[2:3], -1
	s_waitcnt lgkmcnt(0)
	v_cmp_lt_i32_e32 vcc, s21, v0
	v_readfirstlane_b32 s1, v0
	s_cbranch_vccnz .LBB0_1718
	s_waitcnt vmcnt(1)
	v_mov_b32_e32 v120, v176
	s_ashr_i32 s33, s1, 4
	s_sub_i32 s0, 31, s33
	v_readfirstlane_b32 s2, v120
	s_lshl_b32 s3, s1, 10
	s_lshl_b32 s6, s0, 7
	s_ashr_i32 s7, s2, 2
	s_and_b32 s34, s3, 0x3000
	v_and_b32_e32 v60, 15, v120
	s_and_b32 s2, s7, -16
	s_add_i32 s10, s6, s34
	s_ashr_i32 s3, s2, 31
	v_or_b32_e32 v0, s10, v60
	v_lshl_add_u64 v[156:157], v[0:1], 0, s[2:3]
	v_mov_b64_e32 v[2:3], s[62:63]
	v_mad_u64_u32 v[4:5], s[2:3], v156, s22, v[2:3]
	s_and_b32 s5, s1, 3
	v_mad_i32_i24 v5, v157, s22, v5
	v_and_b32_e32 v0, 48, v120
	v_lshl_add_u64 v[4:5], v[4:5], 0, v[0:1]
	s_lshl_b32 s10, s5, 9
	v_ashrrev_i32_e32 v14, 4, v120
	v_lshl_add_u64 v[8:9], v[4:5], 0, s[10:11]
	v_add_u32_e32 v4, s34, v14
	s_lshl_b32 s18, s5, 8
	s_mov_b32 s19, s11
	v_mad_i64_i32 v[2:3], s[2:3], v4, s22, v[2:3]
	v_lshlrev_b32_e32 v6, 4, v120
	v_lshl_add_u64 v[2:3], v[2:3], 0, s[18:19]
	v_and_b32_e32 v10, 0xf0, v6
	v_mov_b32_e32 v11, v1
	v_lshl_add_u64 v[116:117], v[2:3], 0, v[10:11]
	s_lshl_b32 s1, s1, 7
	v_ashrrev_i32_e32 v2, 3, v120
	s_and_b32 s10, s1, 0x780
	v_ashrrev_i32_e32 v3, 31, v2
	v_lshl_add_u64 v[4:5], v[2:3], 0, s[10:11]
	v_lshlrev_b64 v[4:5], 13, v[4:5]
	v_lshl_add_u64 v[4:5], s[40:41], 0, v[4:5]
	v_and_b32_e32 v12, 0x70, v6
	v_mov_b32_e32 v13, v1
	v_lshl_add_u64 v[158:159], v[4:5], 0, v[12:13]
	v_add_co_u32_e32 v4, vcc, s23, v116
	global_load_dwordx4 v[36:39], v[158:159], off
	s_nop 0
	v_addc_co_u32_e32 v5, vcc, 0, v117, vcc
	v_add_co_u32_e32 v6, vcc, s24, v116
	v_mul_lo_u32 v2, v2, s27
	s_nop 0
	v_addc_co_u32_e32 v7, vcc, 0, v117, vcc
	global_load_dwordx4 v[40:43], v[4:5], off offset:3072
	global_load_dwordx4 v[44:47], v[6:7], off offset:3072
	v_add_co_u32_e32 v52, vcc, s25, v158
	v_add_u32_e32 v11, 0, v12
	s_nop 0
	v_addc_co_u32_e32 v53, vcc, 0, v159, vcc
	global_load_dwordx4 v[48:51], v[52:53], off
	v_mul_lo_u32 v3, v14, s26
	v_add_u32_e32 v10, 0, v10
	v_and_b32_e32 v173, 64, v12
	v_bfe_u32 v11, v12, 4, 1
	v_lshl_or_b32 v173, v11, 5, v173
	v_bfe_u32 v11, v12, 5, 1
	v_lshl_or_b32 v173, v11, 3, v173
	v_add_u32_e32 v173, v173, v2
	v_add_co_u32_e64 v2, s[2:3], s23, v8
	v_lshl_add_u64 v[28:29], v[8:9], 0, s[12:13]
	v_add_u32_e32 v172, v10, v3
	v_lshlrev_b64 v[118:119], 9, v[156:157]
	v_add_co_u32_e32 v54, vcc, 0xa1000, v116
	v_addc_co_u32_e64 v3, s[2:3], 0, v9, s[2:3]
	global_load_dwordx4 v[4:7], v[28:29], off offset:64
	v_lshl_add_u64 v[56:57], s[38:39], 0, v[118:119]
	v_addc_co_u32_e32 v55, vcc, 0, v117, vcc
	global_load_dwordx4 v[8:11], v[28:29], off offset:128
	global_load_dwordx4 v[12:15], v[28:29], off offset:192
	global_load_dwordx4 v[16:19], v[28:29], off offset:256
	global_load_dwordx4 v[20:23], v[28:29], off offset:320
	global_load_dwordx4 v[24:27], v[28:29], off offset:384
	s_nop 0
	global_load_dwordx4 v[28:31], v[28:29], off offset:448
	s_nop 0
	global_load_dwordx4 v[32:35], v[2:3], off offset:1024
	s_nop 0
	global_load_dwordx2 v[2:3], v[56:57], off
	v_add_co_u32_e32 v58, vcc, 0xf1000, v116
	s_add_i32 s1, s7, s6
	s_nop 0
	v_addc_co_u32_e32 v59, vcc, 0, v117, vcc
	s_cmp_gt_i32 s1, -1
	s_mov_b64 s[2:3], -1
	s_waitcnt vmcnt(11)
	ds_write_b128 v172, v[40:43]
	ds_write_b64 v173, v[36:37] offset:17408
	ds_write_b64 v173, v[38:39] offset:17424
	s_waitcnt vmcnt(10)
	ds_write_b128 v172, v[44:47] offset:8704
	s_waitcnt vmcnt(9)
	ds_write_b64 v173, v[48:49] offset:26624
	ds_write_b64 v173, v[50:51] offset:26640
	s_waitcnt lgkmcnt(0)
	s_barrier
	global_load_dwordx4 v[44:47], v[58:59], off offset:3072
	global_load_dwordx4 v[36:39], v[54:55], off offset:3072
	global_load_dwordx4 v[48:51], v[52:53], off offset:128
	global_load_dwordx4 v[40:43], v[158:159], off offset:128
	global_load_dwordx2 v[162:163], v[56:57], off offset:8
	v_mad_u32_u24 v52, v60, s26, 0
	v_lshlrev_b32_e32 v53, 7, v60
	v_lshrrev_b32_e32 v54, 2, v120
	v_sub_u32_e32 v53, v52, v53
	v_and_b32_e32 v174, 12, v54
	v_add_u32_e32 v175, v52, v0
	v_lshl_add_u32 v177, v174, 2, v53
	s_cbranch_scc0 .LBB0_1726
	ds_read_b128 v[52:55], v175
	ds_read_b128 v[56:59], v175 offset:64
	ds_read_b128 v[60:63], v175 offset:128
	ds_read_b128 v[64:67], v175 offset:192
	ds_read_b128 v[68:71], v175 offset:4352
	ds_read_b128 v[72:75], v175 offset:4416
	ds_read_b128 v[76:79], v175 offset:4480
	ds_read_b128 v[80:83], v175 offset:4544
	s_setprio 1
	s_mov_b32 s6, s4
	s_mov_b32 s7, s4
	s_mov_b32 s5, s4
	v_mov_b64_e32 v[86:87], s[6:7]
	v_mov_b64_e32 v[84:85], s[4:5]
	s_waitcnt vmcnt(6) lgkmcnt(7)
	s_nop 0
	v_mfma_f32_16x16x32_bf16 v[88:91], v[52:55], v[32:35], v[84:87]
	v_mfma_f32_16x16x32_bf16 v[52:55], v[52:55], v[16:19], v[84:87]
	s_waitcnt lgkmcnt(6)
	v_mfma_f32_16x16x32_bf16 v[88:91], v[56:59], v[4:7], v[88:91]
	v_mfma_f32_16x16x32_bf16 v[52:55], v[56:59], v[20:23], v[52:55]
	s_waitcnt lgkmcnt(5)
	v_mfma_f32_16x16x32_bf16 v[56:59], v[60:63], v[8:11], v[88:91]
	v_mfma_f32_16x16x32_bf16 v[52:55], v[60:63], v[24:27], v[52:55]
	s_waitcnt lgkmcnt(4)
	v_mfma_f32_16x16x32_bf16 v[60:63], v[64:67], v[12:15], v[56:59]
	v_mfma_f32_16x16x32_bf16 v[64:67], v[64:67], v[28:31], v[52:55]
	s_setprio 0
	s_nop 3
	ds_read_b128 v[52:55], v175 offset:8704
	ds_read_b128 v[56:59], v175 offset:8768
	ds_read_b128 v[88:91], v175 offset:8832
	ds_read_b128 v[92:95], v175 offset:8896
	s_setprio 1
	s_waitcnt lgkmcnt(7)
	v_mfma_f32_16x16x32_bf16 v[96:99], v[68:71], v[32:35], v[84:87]
	v_mfma_f32_16x16x32_bf16 v[68:71], v[68:71], v[16:19], v[84:87]
	s_waitcnt lgkmcnt(6)
; DEVINL float fexp2(float x) { return __builtin_amdgcn_exp2f(x); }
; #define LDK(DST, KQ) _Pragma("unroll") for (int kc = 0; kc < 4; ++kc) DST[kc] = *(const bf16x8*)(Ks + ((KQ) * 16 + fr) * 136 + kc * 32 + fq * 8)
; DEVINL void attn_item(const Params& p, int item, char* smem, int wv) {
;     ...
;     LDK(kfb, 1); MMS(kfa, 0);
;     LDK(kfa, 2); MMS(kfb, 1);
;     LDK(kfb, 3); MMS(kfa, 2);
;     LDV(vfa, 0); MMS(kfb, 3);
;     bf16x8 pf[2][2];
;     {
;       const unsigned long long msh = mw >> (fq * 4);
;       const int mlo = (int)(unsigned)msh, mhi = (int)(unsigned)(msh >> 32);
;       int mk[4][4];
; #pragma unroll
;       for (int j = 0; j < 4; ++j) {
;         mk[0][j] = __builtin_amdgcn_sbfe(mlo, j, 1); mk[1][j] = __builtin_amdgcn_sbfe(mlo, 16 + j, 1);
;         mk[2][j] = __builtin_amdgcn_sbfe(mhi, j, 1); mk[3][j] = __builtin_amdgcn_sbfe(mhi, 16 + j, 1);
;       }
; #pragma unroll
;       for (int hh = 0; hh < 2; ++hh) {
;         float mx = s[hh][0][0];
; #pragma unroll
;         for (int kq = 0; kq < 4; ++kq)
; #pragma unroll
;           for (int j = 0; j < 4; ++j) mx = fmaxf(mx, s[hh][kq][j]);
;         {
;           auto r1 = __builtin_amdgcn_permlane16_swap(__float_as_uint(mx), __float_as_uint(mx), false, false);
;           mx = fmaxf(__uint_as_float(r1[0]), __uint_as_float(r1[1]));
;           auto r2 = __builtin_amdgcn_permlane32_swap(__float_as_uint(mx), __float_as_uint(mx), false, false);
;           mx = fmaxf(__uint_as_float(r2[0]), __uint_as_float(r2[1]));
;         }
;         if (kt == 0 || __ballot(mx > 8.f)) {
;           const float delta = (kt == 0) ? mx : fmaxf(mx, 0.f);
;           const float alpha = fexp2(-delta);
;           mrun[hh] += delta;
;           lsum[hh] *= alpha;
; #pragma unroll
;           for (int dt = 0; dt < 8; ++dt) o[hh][dt] *= alpha;
; #pragma unroll
;           for (int kq = 0; kq < 4; ++kq)
; #pragma unroll
;             for (int j = 0; j < 4; ++j) s[hh][kq][j] -= delta;
;         }
;         float ps = 0.f;
;         float pv[4][4];
; #pragma unroll
;         for (int kq = 0; kq < 4; ++kq)
; #pragma unroll
;           for (int j = 0; j < 4; ++j) {
;             pv[kq][j] = __uint_as_float(__float_as_uint(fexp2(s[hh][kq][j])) & (unsigned)mk[kq][j]);
;             ps += pv[kq][j];
;           }
	v_mfma_f32_16x16x32_bf16 v[96:99], v[72:75], v[4:7], v[96:99]
	v_mfma_f32_16x16x32_bf16 v[68:71], v[72:75], v[20:23], v[68:71]
	s_waitcnt lgkmcnt(5)
	v_mfma_f32_16x16x32_bf16 v[72:75], v[76:79], v[8:11], v[96:99]
	v_mfma_f32_16x16x32_bf16 v[68:71], v[76:79], v[24:27], v[68:71]
	s_waitcnt lgkmcnt(4)
	v_mfma_f32_16x16x32_bf16 v[72:75], v[80:83], v[12:15], v[72:75]
	v_mfma_f32_16x16x32_bf16 v[68:71], v[80:83], v[28:31], v[68:71]
	s_setprio 0
	ds_read_b128 v[76:79], v175 offset:13056
	ds_read_b128 v[80:83], v175 offset:13120
	ds_read_b128 v[96:99], v175 offset:13184
	ds_read_b128 v[100:103], v175 offset:13248
	s_setprio 1
	s_waitcnt lgkmcnt(7)
	v_mfma_f32_16x16x32_bf16 v[104:107], v[52:55], v[32:35], v[84:87]
	v_mfma_f32_16x16x32_bf16 v[52:55], v[52:55], v[16:19], v[84:87]
	s_waitcnt lgkmcnt(6)
	v_mfma_f32_16x16x32_bf16 v[104:107], v[56:59], v[4:7], v[104:107]
	v_mfma_f32_16x16x32_bf16 v[52:55], v[56:59], v[20:23], v[52:55]
	s_waitcnt lgkmcnt(5)
	v_mfma_f32_16x16x32_bf16 v[56:59], v[88:91], v[8:11], v[104:107]
	v_mfma_f32_16x16x32_bf16 v[52:55], v[88:91], v[24:27], v[52:55]
	s_waitcnt lgkmcnt(4)
	v_mfma_f32_16x16x32_bf16 v[88:91], v[92:95], v[12:15], v[56:59]
	v_mfma_f32_16x16x32_bf16 v[92:95], v[92:95], v[28:31], v[52:55]
	s_setprio 0
	s_nop 2
	s_nop 0
	ds_read_b128 v[52:55], v177 offset:17408
	ds_read_b128 v[56:59], v177 offset:17472
	s_setprio 1
	s_waitcnt lgkmcnt(5)
	v_mfma_f32_16x16x32_bf16 v[104:107], v[76:79], v[32:35], v[84:87]
	v_mfma_f32_16x16x32_bf16 v[76:79], v[76:79], v[16:19], v[84:87]
	s_waitcnt lgkmcnt(4)
	v_mfma_f32_16x16x32_bf16 v[84:87], v[80:83], v[4:7], v[104:107]
	v_mfma_f32_16x16x32_bf16 v[76:79], v[80:83], v[20:23], v[76:79]
	s_waitcnt lgkmcnt(3)
	v_mfma_f32_16x16x32_bf16 v[80:83], v[96:99], v[8:11], v[84:87]
	v_mfma_f32_16x16x32_bf16 v[76:79], v[96:99], v[24:27], v[76:79]
	s_waitcnt lgkmcnt(2)
	v_mfma_f32_16x16x32_bf16 v[80:83], v[100:103], v[12:15], v[80:83]
	v_mfma_f32_16x16x32_bf16 v[76:79], v[100:103], v[28:31], v[76:79]
	s_setprio 0
	s_waitcnt vmcnt(5)
	v_lshrrev_b64 v[2:3], v174, v[2:3]
	v_bfe_i32 v0, v2, 0, 1
	v_bfe_i32 v86, v2, 16, 1
	v_bfe_i32 v87, v3, 0, 1
	v_bfe_i32 v96, v3, 16, 1
	v_bfe_i32 v97, v2, 1, 1
	v_bfe_i32 v98, v2, 17, 1
	v_bfe_i32 v99, v3, 1, 1
	v_bfe_i32 v104, v3, 17, 1
	v_bfe_i32 v100, v2, 2, 1
	v_bfe_i32 v101, v2, 18, 1
	v_bfe_i32 v105, v3, 2, 1
	v_bfe_i32 v106, v3, 18, 1
	v_bfe_i32 v102, v2, 3, 1
	v_bfe_i32 v103, v2, 19, 1
	v_bfe_i32 v107, v3, 3, 1
	v_bfe_i32 v108, v3, 19, 1
	v_max_f32_e32 v3, v60, v60
	v_max_f32_e32 v2, v3, v61
	v_max3_f32 v2, v2, v62, v63
	v_max3_f32 v2, v2, v72, v73
	v_max3_f32 v2, v2, v74, v75
	v_max3_f32 v2, v2, v88, v89
	v_max3_f32 v2, v2, v90, v91
	v_max3_f32 v2, v2, v80, v81
	v_max3_f32 v2, v2, v82, v83
	v_mov_b32_e32 v3, v2
	s_nop 1
	v_permlane16_swap_b32_e32 v2, v3
	v_max_f32_e32 v2, v2, v3
	v_mov_b32_e32 v3, v2
	s_nop 1
	v_permlane32_swap_b32_e32 v2, v3
	v_max_f32_e32 v3, v2, v3
	v_sub_f32_e32 v2, v80, v3
	v_sub_f32_e32 v61, v61, v3
	v_sub_f32_e32 v80, v81, v3
	v_sub_f32_e32 v81, v82, v3
	v_sub_f32_e32 v82, v83, v3
	v_sub_f32_e32 v83, v88, v3
	v_sub_f32_e32 v88, v90, v3
	v_exp_f32_e32 v90, v61
	v_exp_f32_e32 v115, v2
	v_max_f32_e32 v61, v64, v64
	v_max_f32_e32 v2, v61, v65
	v_max3_f32 v2, v2, v66, v67
	v_max3_f32 v2, v2, v68, v69
	v_max3_f32 v2, v2, v70, v71
	v_max3_f32 v2, v2, v92, v93
	v_max3_f32 v2, v2, v94, v95
	v_max3_f32 v2, v2, v76, v77
	v_max3_f32 v2, v2, v78, v79
	v_mov_b32_e32 v61, v2
	s_nop 1
	v_permlane16_swap_b32_e32 v2, v61
	v_max_f32_e32 v2, v2, v61
	v_mov_b32_e32 v61, v2
	s_nop 1
	v_permlane32_swap_b32_e32 v2, v61
	v_max_f32_e32 v2, v2, v61
	v_sub_f32_e32 v60, v60, v3
	v_sub_f32_e32 v64, v64, v2
	v_exp_f32_e32 v60, v60
	v_sub_f32_e32 v65, v65, v2
	v_exp_f32_e32 v64, v64
	v_sub_f32_e32 v62, v62, v3
	v_sub_f32_e32 v66, v66, v2
	v_exp_f32_e32 v65, v65
	v_sub_f32_e32 v85, v89, v3
	v_sub_f32_e32 v89, v91, v3
	v_sub_f32_e32 v63, v63, v3
	v_exp_f32_e32 v91, v62
	v_sub_f32_e32 v67, v67, v2
	v_exp_f32_e32 v66, v66
	v_sub_f32_e32 v72, v72, v3
	v_exp_f32_e32 v109, v63
	v_sub_f32_e32 v61, v68, v2
	v_sub_f32_e32 v62, v69, v2
	v_exp_f32_e32 v67, v67
	v_sub_f32_e32 v73, v73, v3
	v_exp_f32_e32 v72, v72
	v_exp_f32_e32 v113, v83
	v_exp_f32_e32 v125, v82
	v_sub_f32_e32 v82, v92, v2
	v_sub_f32_e32 v83, v93, v2
	v_sub_f32_e32 v63, v70, v2
	v_sub_f32_e32 v68, v71, v2
	v_exp_f32_e32 v70, v61
	v_exp_f32_e32 v71, v62
	v_and_b32_e32 v61, v0, v64
	v_and_b32_e32 v60, v0, v60
	v_and_b32_e32 v62, v97, v90
	v_sub_f32_e32 v74, v74, v3
	v_exp_f32_e32 v110, v73
	v_exp_f32_e32 v121, v80
	v_exp_f32_e32 v124, v81
	v_sub_f32_e32 v122, v76, v2
	v_sub_f32_e32 v126, v78, v2
	v_exp_f32_e32 v76, v63
	v_exp_f32_e32 v78, v68
	v_and_b32_e32 v63, v97, v65
	v_cvt_pk_bf16_f32 v68, v60, v62
	v_pk_add_f32 v[80:81], v[60:61], 0 op_sel_hi:[1,0]
	v_exp_f32_e32 v0, v82
	v_exp_f32_e32 v60, v83
	v_sub_f32_e32 v75, v75, v3
	v_exp_f32_e32 v111, v74
	v_and_b32_e32 v65, v100, v66
	v_and_b32_e32 v64, v100, v91
	v_pk_add_f32 v[80:81], v[80:81], v[62:63]
	v_exp_f32_e32 v112, v75
	v_and_b32_e32 v67, v102, v67
	v_and_b32_e32 v66, v102, v109
	v_pk_add_f32 v[80:81], v[80:81], v[64:65]
	v_sub_f32_e32 v93, v95, v2
	v_and_b32_e32 v73, v86, v70
	v_and_b32_e32 v72, v86, v72
	v_pk_add_f32 v[80:81], v[80:81], v[66:67]
	v_exp_f32_e32 v114, v85
	v_sub_f32_e32 v92, v94, v2
	v_and_b32_e32 v75, v98, v71
	v_and_b32_e32 v74, v98, v110
	v_pk_add_f32 v[80:81], v[80:81], v[72:73]
	v_and_b32_e32 v83, v87, v0
	v_and_b32_e32 v82, v87, v113
	v_and_b32_e32 v87, v99, v60
	v_exp_f32_e32 v60, v93
	v_exp_f32_e32 v88, v88
; DEVINL float fexp2(float x) { return __builtin_amdgcn_exp2f(x); }
; DEVINL uint32_t pk2(float a, float b) { hwf2 v = {a, b}; hwbf2 r = __builtin_convertvector(v, hwbf2); return *(uint32_t*)&r; }
; #define MMV(SRC, DT) do { __builtin_amdgcn_s_setprio(1); _Pragma("unroll") for (int c2 = 0; c2 < 2; ++c2) { o[0][DT] = mfma16(SRC[c2], pf[0][c2], o[0][DT]); o[1][DT] = mfma16(SRC[c2], pf[1][c2], o[1][DT]); } __builtin_amdgcn_s_setprio(0); } while (0)
; DEVINL void attn_item(const Params& p, int item, char* smem, int wv) {
;     ...
;         float ps = 0.f;
;         float pv[4][4];
; #pragma unroll
;         for (int kq = 0; kq < 4; ++kq)
; #pragma unroll
;           for (int j = 0; j < 4; ++j) {
;             pv[kq][j] = __uint_as_float(__float_as_uint(fexp2(s[hh][kq][j])) & (unsigned)mk[kq][j]);
;             ps += pv[kq][j];
;           }
; #pragma unroll
;         for (int c2 = 0; c2 < 2; ++c2) {
;           u32x4 pw;
;           pw[0] = pk2(pv[2 * c2][0], pv[2 * c2][1]); pw[1] = pk2(pv[2 * c2][2], pv[2 * c2][3]);
;           pw[2] = pk2(pv[2 * c2 + 1][0], pv[2 * c2 + 1][1]); pw[3] = pk2(pv[2 * c2 + 1][2], pv[2 * c2 + 1][3]);
;           pf[hh][c2] = *(bf16x8*)&pw;
;         }
;         lsum[hh] += ps;
;       }
;     }
;     LDV(vfb, 1); MMV(vfa, 0);
;     LDV(vfa, 2); MMV(vfb, 1);
;     LDV(vfb, 3); MMV(vfa, 2);
;     LDV(vfa, 4); MMV(vfb, 3);
;     LDV(vfb, 5); MMV(vfa, 4);
;     LDV(vfa, 6); MMV(vfb, 5);
;     LDV(vfb, 7); MMV(vfa, 6);
;     MMV(vfb, 7);
	v_sub_f32_e32 v123, v77, v2
	v_and_b32_e32 v77, v101, v76
	v_and_b32_e32 v76, v101, v111
	v_pk_add_f32 v[80:81], v[80:81], v[74:75]
	v_exp_f32_e32 v0, v92
	v_exp_f32_e32 v89, v89
	v_sub_f32_e32 v127, v79, v2
	v_and_b32_e32 v79, v103, v78
	v_and_b32_e32 v78, v103, v112
	v_pk_add_f32 v[80:81], v[80:81], v[76:77]
	v_exp_f32_e32 v62, v122
	v_pk_add_f32 v[80:81], v[80:81], v[78:79]
	v_cvt_pk_bf16_f32 v69, v64, v66
	v_and_b32_e32 v86, v99, v114
	v_exp_f32_e32 v64, v123
	v_cvt_pk_bf16_f32 v100, v61, v63
	v_cvt_pk_bf16_f32 v102, v73, v75
	v_and_b32_e32 v75, v107, v60
	v_pk_add_f32 v[60:61], v[80:81], v[82:83]
	v_cvt_pk_bf16_f32 v70, v72, v74
	v_exp_f32_e32 v66, v126
	v_and_b32_e32 v73, v105, v0
	v_and_b32_e32 v72, v105, v88
	v_pk_add_f32 v[60:61], v[60:61], v[86:87]
	v_exp_f32_e32 v90, v127
	v_and_b32_e32 v74, v107, v89
	v_pk_add_f32 v[60:61], v[60:61], v[72:73]
	v_cvt_pk_bf16_f32 v71, v76, v78
	v_cvt_pk_bf16_f32 v103, v77, v79
	v_and_b32_e32 v77, v96, v62
	v_and_b32_e32 v76, v96, v115
	v_pk_add_f32 v[60:61], v[60:61], v[74:75]
	v_and_b32_e32 v79, v104, v64
	v_and_b32_e32 v78, v104, v121
	v_pk_add_f32 v[60:61], v[60:61], v[76:77]
	v_and_b32_e32 v89, v106, v66
	v_and_b32_e32 v88, v106, v124
	v_pk_add_f32 v[60:61], v[60:61], v[78:79]
	v_and_b32_e32 v91, v108, v90
	v_and_b32_e32 v90, v108, v125
	v_pk_add_f32 v[60:61], v[60:61], v[88:89]
	v_exp_f32_e64 v84, -v3
	v_exp_f32_e64 v85, -v2
	v_cvt_pk_bf16_f32 v101, v65, v67
	v_pk_add_f32 v[80:81], v[60:61], v[90:91]
	ds_read_b128 v[60:63], v177 offset:19712
	ds_read_b128 v[64:67], v177 offset:19776
	v_pk_add_f32 v[2:3], v[2:3], 0 op_sel_hi:[1,0]
	v_pk_mul_f32 v[122:123], v[84:85], 0 op_sel_hi:[1,0]
	v_pk_fma_f32 v[160:161], v[84:85], 0, v[80:81] op_sel_hi:[1,0,1]
	v_mov_b32_e32 v126, v122
	v_mov_b32_e32 v127, v122
	v_mov_b32_e32 v128, v122
	v_mov_b32_e32 v129, v122
	v_cvt_pk_bf16_f32 v130, v82, v86
	v_cvt_pk_bf16_f32 v131, v72, v74
	v_cvt_pk_bf16_f32 v132, v76, v78
	v_cvt_pk_bf16_f32 v133, v88, v90
	v_mov_b32_e32 v122, v123
	v_mov_b32_e32 v124, v123
	v_mov_b32_e32 v125, v123
	v_cvt_pk_bf16_f32 v134, v83, v87
	v_cvt_pk_bf16_f32 v135, v73, v75
	v_cvt_pk_bf16_f32 v136, v77, v79
	v_cvt_pk_bf16_f32 v137, v89, v91
	s_setprio 1
	s_waitcnt lgkmcnt(3)
	v_mfma_f32_16x16x32_bf16 v[72:75], v[52:55], v[68:71], v[126:129]
	v_mfma_f32_16x16x32_bf16 v[52:55], v[52:55], v[100:103], v[122:125]
	s_waitcnt lgkmcnt(2)
	v_mfma_f32_16x16x32_bf16 v[88:91], v[56:59], v[130:133], v[72:75]
	v_mfma_f32_16x16x32_bf16 v[52:55], v[56:59], v[134:137], v[52:55]
	s_setprio 0
	s_nop 1
	s_nop 0
	ds_read_b128 v[72:75], v177 offset:22016
	ds_read_b128 v[76:79], v177 offset:22080
	s_setprio 1
	s_waitcnt lgkmcnt(3)
	v_mfma_f32_16x16x32_bf16 v[56:59], v[60:63], v[68:71], v[126:129]
	v_mfma_f32_16x16x32_bf16 v[60:63], v[60:63], v[100:103], v[122:125]
	s_waitcnt lgkmcnt(2)
	v_mfma_f32_16x16x32_bf16 v[84:87], v[64:67], v[130:133], v[56:59]
	v_mfma_f32_16x16x32_bf16 v[56:59], v[64:67], v[134:137], v[60:63]
	s_setprio 0
	ds_read_b128 v[64:67], v177 offset:24320
	ds_read_b128 v[80:83], v177 offset:24384
	s_setprio 1
	s_waitcnt lgkmcnt(3)
	v_mfma_f32_16x16x32_bf16 v[60:63], v[72:75], v[68:71], v[126:129]
	v_mfma_f32_16x16x32_bf16 v[72:75], v[72:75], v[100:103], v[122:125]
	s_waitcnt lgkmcnt(2)
	v_mfma_f32_16x16x32_bf16 v[92:95], v[76:79], v[130:133], v[60:63]
	v_mfma_f32_16x16x32_bf16 v[60:63], v[76:79], v[134:137], v[72:75]
	s_setprio 0
	s_nop 2
	s_nop 0
	ds_read_b128 v[72:75], v177 offset:26624
	ds_read_b128 v[76:79], v177 offset:26688
	s_setprio 1
	s_waitcnt lgkmcnt(3)
	v_mfma_f32_16x16x32_bf16 v[96:99], v[64:67], v[68:71], v[126:129]
	v_mfma_f32_16x16x32_bf16 v[64:67], v[64:67], v[100:103], v[122:125]
	s_waitcnt lgkmcnt(2)
	v_mfma_f32_16x16x32_bf16 v[96:99], v[80:83], v[130:133], v[96:99]
	v_mfma_f32_16x16x32_bf16 v[64:67], v[80:83], v[134:137], v[64:67]
	s_setprio 0
	ds_read_b128 v[80:83], v177 offset:28928
	ds_read_b128 v[112:115], v177 offset:28992
	s_setprio 1
	s_waitcnt lgkmcnt(3)
	v_mfma_f32_16x16x32_bf16 v[104:107], v[72:75], v[68:71], v[126:129]
	v_mfma_f32_16x16x32_bf16 v[72:75], v[72:75], v[100:103], v[122:125]
	s_waitcnt lgkmcnt(2)
	v_mfma_f32_16x16x32_bf16 v[104:107], v[76:79], v[130:133], v[104:107]
	v_mfma_f32_16x16x32_bf16 v[72:75], v[76:79], v[134:137], v[72:75]
	s_setprio 0
	ds_read_b128 v[138:141], v177 offset:31232
	ds_read_b128 v[142:145], v177 offset:31296
	s_setprio 1
	s_waitcnt lgkmcnt(3)
	v_mfma_f32_16x16x32_bf16 v[76:79], v[80:83], v[68:71], v[126:129]
	v_mfma_f32_16x16x32_bf16 v[80:83], v[80:83], v[100:103], v[122:125]
	s_waitcnt lgkmcnt(2)
	v_mfma_f32_16x16x32_bf16 v[108:111], v[112:115], v[130:133], v[76:79]
	v_mfma_f32_16x16x32_bf16 v[76:79], v[112:115], v[134:137], v[80:83]
	s_setprio 0
	ds_read_b128 v[146:149], v177 offset:33536
	ds_read_b128 v[150:153], v177 offset:33600
	s_setprio 1
	s_waitcnt lgkmcnt(3)
	v_mfma_f32_16x16x32_bf16 v[80:83], v[138:141], v[68:71], v[126:129]
	v_mfma_f32_16x16x32_bf16 v[138:141], v[138:141], v[100:103], v[122:125]
	s_waitcnt lgkmcnt(2)
	v_mfma_f32_16x16x32_bf16 v[112:115], v[142:145], v[130:133], v[80:83]
	v_mfma_f32_16x16x32_bf16 v[80:83], v[142:145], v[134:137], v[138:141]
	s_setprio 0
	s_setprio 1
	s_waitcnt lgkmcnt(1)
	v_mfma_f32_16x16x32_bf16 v[68:71], v[146:149], v[68:71], v[126:129]
	v_mfma_f32_16x16x32_bf16 v[122:125], v[146:149], v[100:103], v[122:125]
	s_waitcnt lgkmcnt(0)
	v_mfma_f32_16x16x32_bf16 v[100:103], v[150:153], v[130:133], v[68:71]
	v_mfma_f32_16x16x32_bf16 v[68:71], v[150:153], v[134:137], v[122:125]
	s_setprio 0
	s_cbranch_execz .LBB0_1727
	s_branch .LBB0_1728

; DEVINL float fexp2(float x) { return __builtin_amdgcn_exp2f(x); }
; #define LDK(DST, KQ) _Pragma("unroll") for (int kc = 0; kc < 4; ++kc) DST[kc] = *(const bf16x8*)(Ks + ((KQ) * 16 + fr) * 136 + kc * 32 + fq * 8)
; DEVINL void attn_item(const Params& p, int item, char* smem, int wv) {
;     ...
;     if (kt * 64 <= qlast) {
;     f32x4 s[2][4];
;     bf16x8 kfa[4], kfb[4];
;     bf16x8 vfa[2], vfb[2];
;     ...
;     LDK(kfa, 0);
;     LDK(kfb, 1); MMS(kfa, 0);
;     LDK(kfa, 2); MMS(kfb, 1);
;     LDK(kfb, 3); MMS(kfa, 2);
;     LDV(vfa, 0); MMS(kfb, 3);
;     bf16x8 pf[2][2];
;     {
;       const unsigned long long msh = mw >> (fq * 4);
;       const int mlo = (int)(unsigned)msh, mhi = (int)(unsigned)(msh >> 32);
;       int mk[4][4];
; #pragma unroll
;       for (int j = 0; j < 4; ++j) {
;         mk[0][j] = __builtin_amdgcn_sbfe(mlo, j, 1); mk[1][j] = __builtin_amdgcn_sbfe(mlo, 16 + j, 1);
;         mk[2][j] = __builtin_amdgcn_sbfe(mhi, j, 1); mk[3][j] = __builtin_amdgcn_sbfe(mhi, 16 + j, 1);
;       }
; #pragma unroll
;       for (int hh = 0; hh < 2; ++hh) {
;         float mx = s[hh][0][0];
; #pragma unroll
;         for (int kq = 0; kq < 4; ++kq)
; #pragma unroll
;           for (int j = 0; j < 4; ++j) mx = fmaxf(mx, s[hh][kq][j]);
;         {
;           auto r1 = __builtin_amdgcn_permlane16_swap(__float_as_uint(mx), __float_as_uint(mx), false, false);
;           mx = fmaxf(__uint_as_float(r1[0]), __uint_as_float(r1[1]));
;           auto r2 = __builtin_amdgcn_permlane32_swap(__float_as_uint(mx), __float_as_uint(mx), false, false);
;           mx = fmaxf(__uint_as_float(r2[0]), __uint_as_float(r2[1]));
;         }
;         if (kt == 0 || __ballot(mx > 8.f)) {
;           const float delta = (kt == 0) ? mx : fmaxf(mx, 0.f);
;           const float alpha = fexp2(-delta);
;           mrun[hh] += delta;
;           lsum[hh] *= alpha;
; #pragma unroll
;           for (int dt = 0; dt < 8; ++dt) o[hh][dt] *= alpha;
; #pragma unroll
;           for (int kq = 0; kq < 4; ++kq)
; #pragma unroll
;             for (int j = 0; j < 4; ++j) s[hh][kq][j] -= delta;
;         }
.LBB0_1731:
	s_add_i32 s6, s3, 0xffffffa0
	s_cmp_gt_i32 s6, s1
	s_cbranch_scc1 .LBB0_1737
	ds_read_b128 v[116:119], v175
	ds_read_b128 v[120:123], v175 offset:64
	ds_read_b128 v[124:127], v175 offset:128
	ds_read_b128 v[128:131], v175 offset:192
	ds_read_b128 v[132:135], v175 offset:4352
	ds_read_b128 v[140:143], v175 offset:4416
	ds_read_b128 v[144:147], v175 offset:4480
	ds_read_b128 v[178:181], v175 offset:4544
	v_xor_b32_e32 v182, 0x80000000, v3
	v_xor_b32_e32 v186, 0x80000000, v2
	v_mov_b32_e32 v183, v182
	v_mov_b32_e32 v184, v182
	v_mov_b32_e32 v185, v182
	v_mov_b32_e32 v187, v186
	v_mov_b32_e32 v188, v186
	v_mov_b32_e32 v189, v186
	s_setprio 1
	s_waitcnt lgkmcnt(7)
	v_mfma_f32_16x16x32_bf16 v[136:139], v[116:119], v[32:35], v[182:185]
	v_mfma_f32_16x16x32_bf16 v[116:119], v[116:119], v[16:19], v[186:189]
	s_waitcnt lgkmcnt(6)
	v_mfma_f32_16x16x32_bf16 v[136:139], v[120:123], v[4:7], v[136:139]
	v_mfma_f32_16x16x32_bf16 v[116:119], v[120:123], v[20:23], v[116:119]
	s_waitcnt lgkmcnt(5)
	v_mfma_f32_16x16x32_bf16 v[120:123], v[124:127], v[8:11], v[136:139]
	v_mfma_f32_16x16x32_bf16 v[116:119], v[124:127], v[24:27], v[116:119]
	s_waitcnt lgkmcnt(4)
	v_mfma_f32_16x16x32_bf16 v[152:155], v[128:131], v[12:15], v[120:123]
	v_mfma_f32_16x16x32_bf16 v[136:139], v[128:131], v[28:31], v[116:119]
	s_setprio 0
	s_nop 3
	ds_read_b128 v[116:119], v175 offset:8704
	ds_read_b128 v[120:123], v175 offset:8768
	ds_read_b128 v[124:127], v175 offset:8832
	ds_read_b128 v[128:131], v175 offset:8896
	s_setprio 1
	s_waitcnt lgkmcnt(7)
	v_mfma_f32_16x16x32_bf16 v[148:151], v[132:135], v[32:35], v[182:185]
	v_mfma_f32_16x16x32_bf16 v[132:135], v[132:135], v[16:19], v[186:189]
	s_waitcnt lgkmcnt(6)
	v_mfma_f32_16x16x32_bf16 v[148:151], v[140:143], v[4:7], v[148:151]
	v_mfma_f32_16x16x32_bf16 v[132:135], v[140:143], v[20:23], v[132:135]
	s_waitcnt lgkmcnt(5)
	v_mfma_f32_16x16x32_bf16 v[140:143], v[144:147], v[8:11], v[148:151]
	v_mfma_f32_16x16x32_bf16 v[132:135], v[144:147], v[24:27], v[132:135]
	s_waitcnt lgkmcnt(4)
	v_mfma_f32_16x16x32_bf16 v[148:151], v[178:181], v[12:15], v[140:143]
	v_mfma_f32_16x16x32_bf16 v[132:135], v[178:181], v[28:31], v[132:135]
	s_setprio 0
	ds_read_b128 v[144:147], v175 offset:13056
	ds_read_b128 v[178:181], v175 offset:13120
	ds_read_b128 v[190:193], v175 offset:13184
	ds_read_b128 v[194:197], v175 offset:13248
	s_setprio 1
	s_waitcnt lgkmcnt(7)
	v_mfma_f32_16x16x32_bf16 v[140:143], v[116:119], v[32:35], v[182:185]
	v_mfma_f32_16x16x32_bf16 v[116:119], v[116:119], v[16:19], v[186:189]
	s_waitcnt lgkmcnt(6)
	v_mfma_f32_16x16x32_bf16 v[140:143], v[120:123], v[4:7], v[140:143]
	v_mfma_f32_16x16x32_bf16 v[116:119], v[120:123], v[20:23], v[116:119]
	s_waitcnt lgkmcnt(5)
	v_mfma_f32_16x16x32_bf16 v[120:123], v[124:127], v[8:11], v[140:143]
	v_mfma_f32_16x16x32_bf16 v[116:119], v[124:127], v[24:27], v[116:119]
	s_waitcnt lgkmcnt(4)
	v_mfma_f32_16x16x32_bf16 v[140:143], v[128:131], v[12:15], v[120:123]
	v_mfma_f32_16x16x32_bf16 v[124:127], v[128:131], v[28:31], v[116:119]
	s_setprio 0
	s_nop 2
	s_nop 0
	ds_read_b128 v[116:119], v177 offset:17408
	ds_read_b128 v[120:123], v177 offset:17472
	s_setprio 1
	s_waitcnt lgkmcnt(5)
	v_mfma_f32_16x16x32_bf16 v[128:131], v[144:147], v[32:35], v[182:185]
	v_mfma_f32_16x16x32_bf16 v[144:147], v[144:147], v[16:19], v[186:189]
	s_waitcnt lgkmcnt(4)
	v_mfma_f32_16x16x32_bf16 v[128:131], v[178:181], v[4:7], v[128:131]
	v_mfma_f32_16x16x32_bf16 v[144:147], v[178:181], v[20:23], v[144:147]
	s_waitcnt lgkmcnt(3)
	v_mfma_f32_16x16x32_bf16 v[128:131], v[190:193], v[8:11], v[128:131]
	v_mfma_f32_16x16x32_bf16 v[178:181], v[190:193], v[24:27], v[144:147]
	s_waitcnt lgkmcnt(2)
	v_mfma_f32_16x16x32_bf16 v[144:147], v[194:197], v[12:15], v[128:131]
	v_mfma_f32_16x16x32_bf16 v[128:131], v[194:197], v[28:31], v[178:181]
	s_setprio 0
	s_nop 3
	v_max_f32_e32 v179, v152, v152
	v_max_f32_e32 v178, v179, v153
	v_max3_f32 v178, v178, v154, v155
	v_max3_f32 v178, v178, v148, v149
	v_max3_f32 v178, v178, v150, v151
	v_max3_f32 v178, v178, v140, v141
	v_max3_f32 v178, v178, v142, v143
	v_max3_f32 v178, v178, v144, v145
	v_max3_f32 v178, v178, v146, v147
	v_mov_b32_e32 v179, v178
	s_nop 1
	v_permlane16_swap_b32_e32 v178, v179
	v_max_f32_e32 v178, v178, v179
	v_mov_b32_e32 v179, v178
	s_nop 1
	v_permlane32_swap_b32_e32 v178, v179
	v_max_f32_e32 v178, v178, v179
	v_cmp_lt_f32_e32 vcc, s28, v178
	s_cbranch_vccz .LBB0_1734
	v_max_f32_e32 v178, 0, v178
	v_exp_f32_e64 v180, -v178
	v_add_f32_e32 v3, v3, v178
	v_pk_add_f32 v[152:153], v[152:153], v[178:179] op_sel_hi:[1,0] neg_lo:[0,1] neg_hi:[0,1]
	v_pk_add_f32 v[154:155], v[154:155], v[178:179] op_sel_hi:[1,0] neg_lo:[0,1] neg_hi:[0,1]
	v_mul_f32_e32 v160, v160, v180
	v_pk_mul_f32 v[90:91], v[90:91], v[180:181] op_sel_hi:[1,0]
	v_pk_mul_f32 v[88:89], v[88:89], v[180:181] op_sel_hi:[1,0]
	v_pk_mul_f32 v[86:87], v[86:87], v[180:181] op_sel_hi:[1,0]
	v_pk_mul_f32 v[84:85], v[84:85], v[180:181] op_sel_hi:[1,0]
	v_pk_mul_f32 v[94:95], v[94:95], v[180:181] op_sel_hi:[1,0]
	v_pk_mul_f32 v[92:93], v[92:93], v[180:181] op_sel_hi:[1,0]
	v_pk_mul_f32 v[98:99], v[98:99], v[180:181] op_sel_hi:[1,0]
	v_pk_mul_f32 v[96:97], v[96:97], v[180:181] op_sel_hi:[1,0]
	v_pk_mul_f32 v[106:107], v[106:107], v[180:181] op_sel_hi:[1,0]
	v_pk_mul_f32 v[104:105], v[104:105], v[180:181] op_sel_hi:[1,0]
	v_pk_mul_f32 v[110:111], v[110:111], v[180:181] op_sel_hi:[1,0]
	v_pk_mul_f32 v[108:109], v[108:109], v[180:181] op_sel_hi:[1,0]
	v_pk_mul_f32 v[114:115], v[114:115], v[180:181] op_sel_hi:[1,0]
	v_pk_mul_f32 v[112:113], v[112:113], v[180:181] op_sel_hi:[1,0]
	v_pk_mul_f32 v[102:103], v[102:103], v[180:181] op_sel_hi:[1,0]
	v_pk_mul_f32 v[100:101], v[100:101], v[180:181] op_sel_hi:[1,0]
	v_pk_add_f32 v[148:149], v[148:149], v[178:179] op_sel_hi:[1,0] neg_lo:[0,1] neg_hi:[0,1]
	v_pk_add_f32 v[150:151], v[150:151], v[178:179] op_sel_hi:[1,0] neg_lo:[0,1] neg_hi:[0,1]
	v_pk_add_f32 v[140:141], v[140:141], v[178:179] op_sel_hi:[1,0] neg_lo:[0,1] neg_hi:[0,1]
	v_pk_add_f32 v[142:143], v[142:143], v[178:179] op_sel_hi:[1,0] neg_lo:[0,1] neg_hi:[0,1]
	v_pk_add_f32 v[144:145], v[144:145], v[178:179] op_sel_hi:[1,0] neg_lo:[0,1] neg_hi:[0,1]
	v_pk_add_f32 v[146:147], v[146:147], v[178:179] op_sel_hi:[1,0] neg_lo:[0,1] neg_hi:[0,1]
